# attention unit epilogue: 160 ds_bpermute lane exchanges replaced by DPP moves (quad_perm / row_half_mirror / row_mirror), on top of address diets + static prio
# speedup vs baseline: 1.0053x; 1.0017x over previous
.LBB0_206:
	s_waitcnt lgkmcnt(0)
	s_barrier
	s_cmpk_gt_u32 s54, 0xff
	s_cbranch_scc1 .LBB0_181
	s_add_i32 s8, s58, 0
	s_add_i32 s8, s8, 0x20c00
	v_mov_b32_e32 v78, s8
	ds_read_b32 v78, v78
	ds_read_b128 v[86:89], v146
	ds_read_b128 v[94:97], v146 offset:1024
	v_lshlrev_b32_e32 v79, 2, v226
	v_xor_b32_e32 v142, 4, v79
	v_xor_b32_e32 v144, 8, v79
	v_xor_b32_e32 v143, 16, v79
	v_xor_b32_e32 v145, 32, v79
	v_and_b32_e32 v79, 1, v226
	s_waitcnt lgkmcnt(0)
	v_xor_b32_e32 v81, 0x80000000, v89
	v_xor_b32_e32 v80, 0x80000000, v88
	v_pk_fma_f32 v[140:141], v[86:87], v[78:79], v[218:219] op_sel_hi:[1,0,1] neg_lo:[1,0,0] neg_hi:[1,0,0]
	ds_read_b128 v[86:89], v146 offset:2048
	v_pk_fma_f32 v[136:137], v[78:79], v[94:95], v[214:215] op_sel_hi:[0,1,1] neg_lo:[1,0,0] neg_hi:[1,0,0]
	v_pk_mul_f32 v[94:95], v[136:137], v[136:137]
	v_pk_fma_f32 v[134:135], v[78:79], v[96:97], v[216:217] op_sel_hi:[0,1,1] neg_lo:[1,0,0] neg_hi:[1,0,0]
	v_pk_fma_f32 v[102:103], v[140:141], v[140:141], v[94:95]
	ds_read_b128 v[94:97], v146 offset:3072
	s_waitcnt lgkmcnt(0)
	v_pk_fma_f32 v[130:131], v[78:79], v[88:89], v[212:213] op_sel_hi:[0,1,1] neg_lo:[1,0,0] neg_hi:[1,0,0]
	v_pk_fma_f32 v[132:133], v[78:79], v[86:87], v[210:211] op_sel_hi:[0,1,1] neg_lo:[1,0,0] neg_hi:[1,0,0]
	ds_read_b128 v[86:89], v146 offset:4096
	v_pk_fma_f32 v[102:103], v[132:133], v[132:133], v[102:103]
	v_pk_fma_f32 v[128:129], v[78:79], v[94:95], v[206:207] op_sel_hi:[0,1,1] neg_lo:[1,0,0] neg_hi:[1,0,0]
	v_pk_fma_f32 v[126:127], v[78:79], v[96:97], v[208:209] op_sel_hi:[0,1,1] neg_lo:[1,0,0] neg_hi:[1,0,0]
	v_pk_fma_f32 v[102:103], v[128:129], v[128:129], v[102:103]
	ds_read_b128 v[94:97], v146 offset:5120
	s_waitcnt lgkmcnt(0)
	v_pk_fma_f32 v[124:125], v[78:79], v[86:87], v[202:203] op_sel_hi:[0,1,1] neg_lo:[1,0,0] neg_hi:[1,0,0]
	v_pk_fma_f32 v[138:139], v[80:81], v[78:79], v[220:221] op_sel_hi:[1,0,1]
	v_pk_mul_f32 v[80:81], v[134:135], v[134:135]
	v_pk_fma_f32 v[86:87], v[124:125], v[124:125], v[102:103]
	ds_read_b128 v[102:105], v146 offset:6144
	ds_read_b128 v[106:109], v146 offset:7168
	ds_read_b128 v[148:151], v146 offset:8192
	v_pk_fma_f32 v[80:81], v[138:139], v[138:139], v[80:81]
	v_and_b32_e32 v147, 15, v226
	v_pk_fma_f32 v[80:81], v[130:131], v[130:131], v[80:81]
	v_pk_fma_f32 v[120:121], v[78:79], v[88:89], v[204:205] op_sel_hi:[0,1,1] neg_lo:[1,0,0] neg_hi:[1,0,0]
	v_pk_fma_f32 v[80:81], v[126:127], v[126:127], v[80:81]
	ds_read_b128 v[152:155], v146 offset:9216
	ds_read_b128 v[156:159], v146 offset:10240
	v_pk_fma_f32 v[80:81], v[120:121], v[120:121], v[80:81]
	v_pk_fma_f32 v[116:117], v[78:79], v[96:97], v[200:201] op_sel_hi:[0,1,1] neg_lo:[1,0,0] neg_hi:[1,0,0]
	v_pk_fma_f32 v[118:119], v[78:79], v[94:95], v[198:199] op_sel_hi:[0,1,1] neg_lo:[1,0,0] neg_hi:[1,0,0]
	v_lshlrev_b32_e32 v222, 2, v147
	v_pk_fma_f32 v[180:181], v[116:117], v[116:117], v[80:81]
	v_pk_fma_f32 v[80:81], v[118:119], v[118:119], v[86:87]
	s_waitcnt lgkmcnt(0)
	v_pk_fma_f32 v[114:115], v[78:79], v[102:103], v[194:195] op_sel_hi:[0,1,1] neg_lo:[1,0,0] neg_hi:[1,0,0]
	v_pk_fma_f32 v[102:103], v[78:79], v[148:149], v[186:187] op_sel_hi:[0,1,1] neg_lo:[1,0,0] neg_hi:[1,0,0]
	ds_read_b128 v[160:163], v146 offset:11264
	ds_read_b128 v[164:167], v146 offset:12288
	global_load_dword v148, v222, s[10:11]
	v_pk_fma_f32 v[80:81], v[114:115], v[114:115], v[80:81]
	v_pk_fma_f32 v[106:107], v[78:79], v[106:107], v[190:191] op_sel_hi:[0,1,1] neg_lo:[1,0,0] neg_hi:[1,0,0]
	v_pk_fma_f32 v[80:81], v[106:107], v[106:107], v[80:81]
	ds_read_b128 v[168:171], v146 offset:13312
	ds_read_b128 v[172:175], v146 offset:14336
	v_pk_fma_f32 v[80:81], v[102:103], v[102:103], v[80:81]
	v_pk_fma_f32 v[96:97], v[78:79], v[152:153], v[110:111] op_sel_hi:[0,1,1] neg_lo:[1,0,0] neg_hi:[1,0,0]
	v_pk_fma_f32 v[80:81], v[96:97], v[96:97], v[80:81]
	v_pk_fma_f32 v[94:95], v[78:79], v[156:157], v[98:99] op_sel_hi:[0,1,1] neg_lo:[1,0,0] neg_hi:[1,0,0]
	ds_read_b128 v[176:179], v146 offset:15360
	v_pk_fma_f32 v[80:81], v[94:95], v[94:95], v[80:81]
	s_waitcnt lgkmcnt(0)
	v_pk_fma_f32 v[88:89], v[78:79], v[160:161], v[90:91] op_sel_hi:[0,1,1] neg_lo:[1,0,0] neg_hi:[1,0,0]
	v_pk_fma_f32 v[80:81], v[88:89], v[88:89], v[80:81]
	v_pk_fma_f32 v[86:87], v[78:79], v[164:165], v[82:83] op_sel_hi:[0,1,1] neg_lo:[1,0,0] neg_hi:[1,0,0]
	s_lshl_b64 s[6:7], s[6:7], 13
	v_pk_fma_f32 v[82:83], v[86:87], v[86:87], v[80:81]
	v_pk_fma_f32 v[80:81], v[78:79], v[168:169], v[74:75] op_sel_hi:[0,1,1] neg_lo:[1,0,0] neg_hi:[1,0,0]
	s_add_u32 s6, s40, s6
	v_pk_fma_f32 v[82:83], v[80:81], v[80:81], v[82:83]
	v_pk_fma_f32 v[74:75], v[78:79], v[172:173], v[70:71] op_sel_hi:[0,1,1] neg_lo:[1,0,0] neg_hi:[1,0,0]
	s_addc_u32 s7, s41, s7
	s_lshl_b32 s8, s55, 1
	v_pk_fma_f32 v[82:83], v[74:75], v[74:75], v[82:83]
	v_pk_fma_f32 v[70:71], v[78:79], v[176:177], v[66:67] op_sel_hi:[0,1,1] neg_lo:[1,0,0] neg_hi:[1,0,0]
	s_add_u32 s34, s6, s8
	v_pk_fma_f32 v[66:67], v[70:71], v[70:71], v[82:83]
	s_addc_u32 s35, s7, 0
	v_cmp_eq_u32_e64 s[6:7], 0, v79
	s_nop 1
	v_mov_b32_dpp v79, v66 quad_perm:[1,0,3,2] row_mask:0xf bank_mask:0xf
	s_waitcnt lgkmcnt(0)
	v_add_f32_e32 v66, v66, v79
	v_pk_fma_f32 v[122:123], v[78:79], v[104:105], v[196:197] op_sel_hi:[0,1,1] neg_lo:[1,0,0] neg_hi:[1,0,0]
	s_nop 1
	v_mov_b32_dpp v79, v66 quad_perm:[2,3,0,1] row_mask:0xf bank_mask:0xf
	v_pk_fma_f32 v[82:83], v[122:123], v[122:123], v[180:181]
	s_waitcnt lgkmcnt(0)
	v_add_f32_e32 v66, v66, v79
	v_pk_fma_f32 v[110:111], v[78:79], v[108:109], v[192:193] op_sel_hi:[0,1,1] neg_lo:[1,0,0] neg_hi:[1,0,0]
	v_pk_fma_f32 v[108:109], v[78:79], v[150:151], v[188:189] op_sel_hi:[0,1,1] neg_lo:[1,0,0] neg_hi:[1,0,0]
	s_nop 1
	v_mov_b32_dpp v79, v66 row_half_mirror row_mask:0xf bank_mask:0xf
	v_pk_fma_f32 v[82:83], v[110:111], v[110:111], v[82:83]
	s_waitcnt lgkmcnt(0)
	v_add_f32_e32 v66, v66, v79
	v_pk_fma_f32 v[104:105], v[78:79], v[154:155], v[112:113] op_sel_hi:[0,1,1] neg_lo:[1,0,0] neg_hi:[1,0,0]
	v_pk_fma_f32 v[98:99], v[78:79], v[158:159], v[100:101] op_sel_hi:[0,1,1] neg_lo:[1,0,0] neg_hi:[1,0,0]
	s_nop 1
	v_mov_b32_dpp v79, v66 row_mirror row_mask:0xf bank_mask:0xf
	v_pk_fma_f32 v[82:83], v[108:109], v[108:109], v[82:83]
	s_waitcnt lgkmcnt(0)
	v_add_f32_e32 v66, v66, v79
	v_fmamk_f32 v66, v66, 0x3b800000, v1
	v_pk_fma_f32 v[90:91], v[78:79], v[162:163], v[92:93] op_sel_hi:[0,1,1] neg_lo:[1,0,0] neg_hi:[1,0,0]
	v_pk_fma_f32 v[84:85], v[78:79], v[166:167], v[84:85] op_sel_hi:[0,1,1] neg_lo:[1,0,0] neg_hi:[1,0,0]
	v_mul_f32_e32 v79, 0x4f800000, v66
	v_cmp_gt_f32_e32 vcc, s53, v66
	v_pk_fma_f32 v[82:83], v[104:105], v[104:105], v[82:83]
	s_nop 0
	v_cndmask_b32_e32 v66, v66, v79, vcc
	v_sqrt_f32_e32 v79, v66
	v_pk_fma_f32 v[82:83], v[98:99], v[98:99], v[82:83]
	s_nop 0
	v_pk_fma_f32 v[82:83], v[90:91], v[90:91], v[82:83]
	s_nop 0
	v_pk_fma_f32 v[92:93], v[84:85], v[84:85], v[82:83]
	v_pk_fma_f32 v[82:83], v[78:79], v[170:171], v[76:77] op_sel_hi:[0,1,1] neg_lo:[1,0,0] neg_hi:[1,0,0]
	v_pk_fma_f32 v[76:77], v[78:79], v[174:175], v[72:73] op_sel_hi:[0,1,1] neg_lo:[1,0,0] neg_hi:[1,0,0]
	v_add_u32_e32 v72, -1, v79
	v_fma_f32 v73, -v72, v79, v66
	v_cmp_ge_f32_e64 s[8:9], 0, v73
	v_add_u32_e32 v73, 1, v79
	v_pk_fma_f32 v[92:93], v[82:83], v[82:83], v[92:93]
	v_cndmask_b32_e64 v72, v79, v72, s[8:9]
	v_fma_f32 v79, -v73, v79, v66
	v_cmp_lt_f32_e64 s[8:9], 0, v79
	v_pk_fma_f32 v[92:93], v[76:77], v[76:77], v[92:93]
	s_nop 0
	v_cndmask_b32_e64 v72, v72, v73, s[8:9]
	v_mul_f32_e32 v73, 0x37800000, v72
	v_cndmask_b32_e32 v72, v72, v73, vcc
	v_cmp_class_f32_e32 vcc, v66, v224
	s_nop 1
	v_cndmask_b32_e32 v66, v72, v66, vcc
	v_div_scale_f32 v79, s[8:9], v66, v66, 1.0
	v_rcp_f32_e32 v100, v79
	v_pk_fma_f32 v[72:73], v[78:79], v[178:179], v[68:69] op_sel_hi:[0,1,1] neg_lo:[1,0,0] neg_hi:[1,0,0]
	v_pk_fma_f32 v[68:69], v[72:73], v[72:73], v[92:93]
	v_fma_f32 v92, -v79, v100, 1.0
	v_fmac_f32_e32 v100, v92, v100
	v_div_scale_f32 v92, vcc, 1.0, v66, 1.0
	v_mul_f32_e32 v93, v92, v100
	v_fma_f32 v101, -v79, v93, v92
	v_fmac_f32_e32 v93, v101, v100
	v_fma_f32 v79, -v79, v93, v92
	v_div_fmas_f32 v79, v79, v100, v93
	s_nop 1
	v_mov_b32_dpp v93, v68 quad_perm:[1,0,3,2] row_mask:0xf bank_mask:0xf
	v_div_fixup_f32 v79, v79, v66, 1.0
	s_nop 1
	v_mov_b32_dpp v66, v69 quad_perm:[1,0,3,2] row_mask:0xf bank_mask:0xf
	s_nop 1
	v_mov_b32_dpp v92, v67 quad_perm:[1,0,3,2] row_mask:0xf bank_mask:0xf
	s_waitcnt lgkmcnt(0)
	v_add_f32_e32 v68, v68, v93
	s_nop 1
	v_mov_b32_dpp v93, v68 quad_perm:[2,3,0,1] row_mask:0xf bank_mask:0xf
	v_add_f32_e32 v66, v69, v66
	v_add_f32_e32 v67, v67, v92
	s_nop 1
	v_mov_b32_dpp v69, v66 quad_perm:[2,3,0,1] row_mask:0xf bank_mask:0xf
	s_nop 1
	v_mov_b32_dpp v92, v67 quad_perm:[2,3,0,1] row_mask:0xf bank_mask:0xf
	s_waitcnt lgkmcnt(0)
	v_add_f32_e32 v68, v68, v93
	s_nop 1
	v_mov_b32_dpp v93, v68 row_half_mirror row_mask:0xf bank_mask:0xf
	v_add_f32_e32 v66, v66, v69
	v_add_f32_e32 v67, v67, v92
	s_nop 1
	v_mov_b32_dpp v69, v66 row_half_mirror row_mask:0xf bank_mask:0xf
	s_nop 1
	v_mov_b32_dpp v92, v67 row_half_mirror row_mask:0xf bank_mask:0xf
	s_waitcnt lgkmcnt(0)
	v_add_f32_e32 v93, v68, v93
	s_waitcnt vmcnt(0)
	v_mul_f32_e32 v68, 0x3f4ccccd, v148
	s_nop 1
	v_mov_b32_dpp v101, v93 row_mirror row_mask:0xf bank_mask:0xf
	v_add_f32_e32 v69, v66, v69
	v_mul_f32_e32 v66, v140, v79
	v_add_f32_e32 v92, v67, v92
	v_mul_f32_e32 v113, v66, v68
	s_nop 1
	v_mov_b32_dpp v112, v92 row_mirror row_mask:0xf bank_mask:0xf
	s_nop 1
	v_mov_b32_dpp v100, v69 row_mirror row_mask:0xf bank_mask:0xf
	s_nop 1
	v_mov_b32_dpp v140, v113 quad_perm:[1,0,3,2] row_mask:0xf bank_mask:0xf
	v_lshlrev_b32_e32 v66, 10, v226
	v_and_or_b32 v66, v66, s52, v147
	v_ashrrev_i32_e32 v67, 31, v66
	v_lshl_add_u64 v[66:67], v[66:67], 1, s[34:35]
	s_and_saveexec_b64 s[8:9], s[6:7]
	s_cbranch_execz .LBB0_209
	s_waitcnt lgkmcnt(0)
	v_cvt_pk_bf16_f32 v113, v113, v140
	global_store_dword v[66:67], v113, off
.LBB0_209:
	s_or_b64 exec, exec, s[8:9]
	s_waitcnt lgkmcnt(0)
	v_add_f32_e32 v92, v92, v112
	v_fmamk_f32 v92, v92, 0x3b800000, v1
	v_mul_f32_e32 v112, 0x4f800000, v92
	v_cmp_gt_f32_e32 vcc, s53, v92
	s_nop 1
	v_cndmask_b32_e32 v92, v92, v112, vcc
	v_sqrt_f32_e32 v112, v92
	s_nop 0
	v_add_u32_e32 v113, -1, v112
	v_fma_f32 v147, -v113, v112, v92
	s_waitcnt lgkmcnt(0)
	v_add_u32_e32 v140, 1, v112
	v_cmp_ge_f32_e64 s[8:9], 0, v147
	s_nop 1
	v_cndmask_b32_e64 v113, v112, v113, s[8:9]
	v_fma_f32 v112, -v140, v112, v92
	v_cmp_lt_f32_e64 s[8:9], 0, v112
	s_nop 1
	v_cndmask_b32_e64 v112, v113, v140, s[8:9]
	v_mul_f32_e32 v113, 0x37800000, v112
	v_cndmask_b32_e32 v112, v112, v113, vcc
	v_cmp_class_f32_e32 vcc, v92, v224
	s_nop 1
	v_cndmask_b32_e32 v92, v112, v92, vcc
	v_div_scale_f32 v112, s[8:9], v92, v92, 1.0
	v_rcp_f32_e32 v113, v112
	s_nop 0
	v_fma_f32 v140, -v112, v113, 1.0
	v_fmac_f32_e32 v113, v140, v113
	v_div_scale_f32 v140, vcc, 1.0, v92, 1.0
	v_mul_f32_e32 v147, v140, v113
	v_fma_f32 v148, -v112, v147, v140
	v_fmac_f32_e32 v147, v148, v113
	v_fma_f32 v112, -v112, v147, v140
	v_div_fmas_f32 v112, v112, v113, v147
	v_div_fixup_f32 v92, v112, v92, 1.0
	v_mul_f32_e32 v112, v141, v92
	v_mul_f32_e32 v112, v112, v68
	s_nop 1
	v_mov_b32_dpp v113, v112 quad_perm:[1,0,3,2] row_mask:0xf bank_mask:0xf
	s_and_saveexec_b64 s[8:9], s[6:7]
	s_cbranch_execz .LBB0_211
	s_waitcnt lgkmcnt(0)
	v_cvt_pk_bf16_f32 v140, v112, v113
	v_add_co_u32_e32 v112, vcc, 0x2000, v66
	s_nop 1
	v_addc_co_u32_e32 v113, vcc, 0, v67, vcc
	global_store_dword v[112:113], v140, off
.LBB0_211:
	s_or_b64 exec, exec, s[8:9]
	v_add_f32_e32 v93, v93, v101
	v_fmamk_f32 v93, v93, 0x3b800000, v1
	v_mul_f32_e32 v101, 0x4f800000, v93
	v_cmp_gt_f32_e32 vcc, s53, v93
	s_nop 1
	v_cndmask_b32_e32 v93, v93, v101, vcc
	v_sqrt_f32_e32 v101, v93
	s_nop 0
	v_add_u32_e32 v112, -1, v101
	v_fma_f32 v140, -v112, v101, v93
	s_waitcnt lgkmcnt(0)
	v_add_u32_e32 v113, 1, v101
	v_cmp_ge_f32_e64 s[8:9], 0, v140
	s_nop 1
	v_cndmask_b32_e64 v112, v101, v112, s[8:9]
	v_fma_f32 v101, -v113, v101, v93
	v_cmp_lt_f32_e64 s[8:9], 0, v101
	s_nop 1
	v_cndmask_b32_e64 v101, v112, v113, s[8:9]
	v_mul_f32_e32 v112, 0x37800000, v101
	v_cndmask_b32_e32 v101, v101, v112, vcc
	v_cmp_class_f32_e32 vcc, v93, v224
	s_nop 1
	v_cndmask_b32_e32 v93, v101, v93, vcc
	v_div_scale_f32 v101, s[8:9], v93, v93, 1.0
	v_rcp_f32_e32 v112, v101
	s_nop 0
	v_fma_f32 v113, -v101, v112, 1.0
	v_fmac_f32_e32 v112, v113, v112
	v_div_scale_f32 v113, vcc, 1.0, v93, 1.0
	v_mul_f32_e32 v140, v113, v112
	v_fma_f32 v141, -v101, v140, v113
	v_fmac_f32_e32 v140, v141, v112
	v_fma_f32 v101, -v101, v140, v113
	v_div_fmas_f32 v101, v101, v112, v140
	v_div_fixup_f32 v93, v101, v93, 1.0
	v_mul_f32_e32 v101, v138, v93
	v_mul_f32_e32 v101, v68, v101
	s_nop 1
	v_mov_b32_dpp v112, v101 quad_perm:[1,0,3,2] row_mask:0xf bank_mask:0xf
	s_and_saveexec_b64 s[8:9], s[6:7]
	s_cbranch_execz .LBB0_213
	s_waitcnt lgkmcnt(0)
	v_cvt_pk_bf16_f32 v101, v101, v112
	v_add_co_u32_e32 v112, vcc, 0x4000, v66
	s_nop 1
	v_addc_co_u32_e32 v113, vcc, 0, v67, vcc
	global_store_dword v[112:113], v101, off
.LBB0_213:
	s_or_b64 exec, exec, s[8:9]
	v_add_f32_e32 v69, v69, v100
	v_fmamk_f32 v69, v69, 0x3b800000, v1
	v_mul_f32_e32 v100, 0x4f800000, v69
	v_cmp_gt_f32_e32 vcc, s53, v69
	s_nop 1
	v_cndmask_b32_e32 v69, v69, v100, vcc
	v_sqrt_f32_e32 v100, v69
	s_nop 0
	v_add_u32_e32 v101, -1, v100
	v_fma_f32 v113, -v101, v100, v69
	s_waitcnt lgkmcnt(0)
	v_add_u32_e32 v112, 1, v100
	v_cmp_ge_f32_e64 s[8:9], 0, v113
	s_nop 1
	v_cndmask_b32_e64 v101, v100, v101, s[8:9]
	v_fma_f32 v100, -v112, v100, v69
	v_cmp_lt_f32_e64 s[8:9], 0, v100
	s_nop 1
	v_cndmask_b32_e64 v100, v101, v112, s[8:9]
	v_mul_f32_e32 v101, 0x37800000, v100
	v_cndmask_b32_e32 v100, v100, v101, vcc
	v_cmp_class_f32_e32 vcc, v69, v224
	s_nop 1
	v_cndmask_b32_e32 v69, v100, v69, vcc
	v_div_scale_f32 v100, s[8:9], v69, v69, 1.0
	v_rcp_f32_e32 v101, v100
	s_nop 0
	v_fma_f32 v112, -v100, v101, 1.0
	v_fmac_f32_e32 v101, v112, v101
	v_div_scale_f32 v112, vcc, 1.0, v69, 1.0
	v_mul_f32_e32 v113, v112, v101
	v_fma_f32 v138, -v100, v113, v112
	v_fmac_f32_e32 v113, v138, v101
	v_fma_f32 v100, -v100, v113, v112
	v_div_fmas_f32 v100, v100, v101, v113
	v_div_fixup_f32 v100, v100, v69, 1.0
	v_mul_f32_e32 v69, v139, v100
	v_mul_f32_e32 v68, v68, v69
	s_nop 1
	v_mov_b32_dpp v69, v68 quad_perm:[1,0,3,2] row_mask:0xf bank_mask:0xf
	s_and_saveexec_b64 s[8:9], s[6:7]
	s_cbranch_execz .LBB0_215
	s_waitcnt lgkmcnt(0)
	v_cvt_pk_bf16_f32 v101, v68, v69
	v_add_co_u32_e32 v68, vcc, 0x6000, v66
	s_nop 1
	v_addc_co_u32_e32 v69, vcc, 0, v67, vcc
	global_store_dword v[68:69], v101, off
.LBB0_215:
	s_or_b64 exec, exec, s[8:9]
	s_waitcnt lgkmcnt(0)
	v_lshl_add_u64 v[68:69], s[10:11], 0, v[222:223]
	global_load_dword v101, v[68:69], off offset:64
	v_mul_f32_e32 v112, v136, v79
	s_waitcnt vmcnt(0)
	v_mul_f32_e32 v101, 0x3f4ccccd, v101
	v_mul_f32_e32 v112, v112, v101
	s_nop 1
	v_mov_b32_dpp v113, v112 quad_perm:[1,0,3,2] row_mask:0xf bank_mask:0xf
	s_and_saveexec_b64 s[8:9], s[6:7]
	s_cbranch_execz .LBB0_217
	s_waitcnt lgkmcnt(0)
	v_cvt_pk_bf16_f32 v112, v112, v113
	global_store_dword v[66:67], v112, off offset:32
.LBB0_217:
	s_or_b64 exec, exec, s[8:9]
	v_mul_f32_e32 v112, v137, v92
	v_mul_f32_e32 v112, v112, v101
	s_waitcnt lgkmcnt(0)
	s_nop 1
	v_mov_b32_dpp v113, v112 quad_perm:[1,0,3,2] row_mask:0xf bank_mask:0xf
	s_and_saveexec_b64 s[8:9], s[6:7]
	s_cbranch_execz .LBB0_219
	s_waitcnt lgkmcnt(0)
	v_cvt_pk_bf16_f32 v136, v112, v113
	v_add_co_u32_e32 v112, vcc, 0x2000, v66
	s_nop 1
	v_addc_co_u32_e32 v113, vcc, 0, v67, vcc
	global_store_dword v[112:113], v136, off offset:32
.LBB0_219:
	s_or_b64 exec, exec, s[8:9]
	v_mul_f32_e32 v112, v134, v93
	v_mul_f32_e32 v112, v112, v101
	s_waitcnt lgkmcnt(0)
	s_nop 1
	v_mov_b32_dpp v113, v112 quad_perm:[1,0,3,2] row_mask:0xf bank_mask:0xf
	s_and_saveexec_b64 s[8:9], s[6:7]
	s_cbranch_execz .LBB0_221
	s_waitcnt lgkmcnt(0)
	v_cvt_pk_bf16_f32 v134, v112, v113
	v_add_co_u32_e32 v112, vcc, 0x4000, v66
	s_nop 1
	v_addc_co_u32_e32 v113, vcc, 0, v67, vcc
	global_store_dword v[112:113], v134, off offset:32
.LBB0_221:
	s_or_b64 exec, exec, s[8:9]
	v_mul_f32_e32 v112, v135, v100
	v_mul_f32_e32 v101, v112, v101
	s_nop 1
	v_mov_b32_dpp v112, v101 quad_perm:[1,0,3,2] row_mask:0xf bank_mask:0xf
	s_and_saveexec_b64 s[8:9], s[6:7]
	s_cbranch_execz .LBB0_223
	s_waitcnt lgkmcnt(0)
	v_cvt_pk_bf16_f32 v101, v101, v112
	v_add_co_u32_e32 v112, vcc, 0x6000, v66
	s_nop 1
	v_addc_co_u32_e32 v113, vcc, 0, v67, vcc
	global_store_dword v[112:113], v101, off offset:32
.LBB0_223:
	s_or_b64 exec, exec, s[8:9]
	global_load_dword v101, v[68:69], off offset:128
	s_waitcnt lgkmcnt(0)
	v_mul_f32_e32 v112, v132, v79
	s_waitcnt vmcnt(0)
	v_mul_f32_e32 v101, 0x3f4ccccd, v101
	v_mul_f32_e32 v112, v112, v101
	s_nop 1
	v_mov_b32_dpp v113, v112 quad_perm:[1,0,3,2] row_mask:0xf bank_mask:0xf
	s_and_saveexec_b64 s[8:9], s[6:7]
	s_cbranch_execz .LBB0_225
	s_waitcnt lgkmcnt(0)
	v_cvt_pk_bf16_f32 v112, v112, v113
	global_store_dword v[66:67], v112, off offset:64
.LBB0_225:
	s_or_b64 exec, exec, s[8:9]
	v_mul_f32_e32 v112, v133, v92
	v_mul_f32_e32 v112, v112, v101
	s_waitcnt lgkmcnt(0)
	s_nop 1
	v_mov_b32_dpp v113, v112 quad_perm:[1,0,3,2] row_mask:0xf bank_mask:0xf
	s_and_saveexec_b64 s[8:9], s[6:7]
	s_cbranch_execz .LBB0_227
	s_waitcnt lgkmcnt(0)
	v_cvt_pk_bf16_f32 v132, v112, v113
	v_add_co_u32_e32 v112, vcc, 0x2000, v66
	s_nop 1
	v_addc_co_u32_e32 v113, vcc, 0, v67, vcc
	global_store_dword v[112:113], v132, off offset:64
.LBB0_227:
	s_or_b64 exec, exec, s[8:9]
	v_mul_f32_e32 v112, v130, v93
	v_mul_f32_e32 v112, v112, v101
	s_waitcnt lgkmcnt(0)
	s_nop 1
	v_mov_b32_dpp v113, v112 quad_perm:[1,0,3,2] row_mask:0xf bank_mask:0xf
	s_and_saveexec_b64 s[8:9], s[6:7]
	s_cbranch_execz .LBB0_229
	s_waitcnt lgkmcnt(0)
	v_cvt_pk_bf16_f32 v130, v112, v113
	v_add_co_u32_e32 v112, vcc, 0x4000, v66
	s_nop 1
	v_addc_co_u32_e32 v113, vcc, 0, v67, vcc
	global_store_dword v[112:113], v130, off offset:64
.LBB0_229:
	s_or_b64 exec, exec, s[8:9]
	v_mul_f32_e32 v112, v131, v100
	v_mul_f32_e32 v101, v112, v101
	s_nop 1
	v_mov_b32_dpp v112, v101 quad_perm:[1,0,3,2] row_mask:0xf bank_mask:0xf
	s_and_saveexec_b64 s[8:9], s[6:7]
	s_cbranch_execz .LBB0_231
	s_waitcnt lgkmcnt(0)
	v_cvt_pk_bf16_f32 v101, v101, v112
	v_add_co_u32_e32 v112, vcc, 0x6000, v66
	s_nop 1
	v_addc_co_u32_e32 v113, vcc, 0, v67, vcc
	global_store_dword v[112:113], v101, off offset:64
.LBB0_231:
	s_or_b64 exec, exec, s[8:9]
	global_load_dword v101, v[68:69], off offset:192
	s_waitcnt lgkmcnt(0)
	v_mul_f32_e32 v112, v128, v79
	s_waitcnt vmcnt(0)
	v_mul_f32_e32 v101, 0x3f4ccccd, v101
	v_mul_f32_e32 v112, v112, v101
	s_nop 1
	v_mov_b32_dpp v113, v112 quad_perm:[1,0,3,2] row_mask:0xf bank_mask:0xf
	s_and_saveexec_b64 s[8:9], s[6:7]
	s_cbranch_execz .LBB0_233
	s_waitcnt lgkmcnt(0)
	v_cvt_pk_bf16_f32 v112, v112, v113
	global_store_dword v[66:67], v112, off offset:96
.LBB0_233:
	s_or_b64 exec, exec, s[8:9]
	v_mul_f32_e32 v112, v129, v92
	v_mul_f32_e32 v112, v112, v101
	s_waitcnt lgkmcnt(0)
	s_nop 1
	v_mov_b32_dpp v113, v112 quad_perm:[1,0,3,2] row_mask:0xf bank_mask:0xf
	s_and_saveexec_b64 s[8:9], s[6:7]
	s_cbranch_execz .LBB0_235
	s_waitcnt lgkmcnt(0)
	v_cvt_pk_bf16_f32 v128, v112, v113
	v_add_co_u32_e32 v112, vcc, 0x2000, v66
	s_nop 1
	v_addc_co_u32_e32 v113, vcc, 0, v67, vcc
	global_store_dword v[112:113], v128, off offset:96
.LBB0_235:
	s_or_b64 exec, exec, s[8:9]
	v_mul_f32_e32 v112, v126, v93
	v_mul_f32_e32 v112, v112, v101
	s_waitcnt lgkmcnt(0)
	s_nop 1
	v_mov_b32_dpp v113, v112 quad_perm:[1,0,3,2] row_mask:0xf bank_mask:0xf
	s_and_saveexec_b64 s[8:9], s[6:7]
	s_cbranch_execz .LBB0_237
	s_waitcnt lgkmcnt(0)
	v_cvt_pk_bf16_f32 v126, v112, v113
	v_add_co_u32_e32 v112, vcc, 0x4000, v66
	s_nop 1
	v_addc_co_u32_e32 v113, vcc, 0, v67, vcc
	global_store_dword v[112:113], v126, off offset:96
.LBB0_237:
	s_or_b64 exec, exec, s[8:9]
	v_mul_f32_e32 v112, v127, v100
	v_mul_f32_e32 v101, v112, v101
	s_nop 1
	v_mov_b32_dpp v112, v101 quad_perm:[1,0,3,2] row_mask:0xf bank_mask:0xf
	s_and_saveexec_b64 s[8:9], s[6:7]
	s_cbranch_execz .LBB0_239
	s_waitcnt lgkmcnt(0)
	v_cvt_pk_bf16_f32 v101, v101, v112
	v_add_co_u32_e32 v112, vcc, 0x6000, v66
	s_nop 1
	v_addc_co_u32_e32 v113, vcc, 0, v67, vcc
	global_store_dword v[112:113], v101, off offset:96
.LBB0_239:
	s_or_b64 exec, exec, s[8:9]
	global_load_dword v101, v[68:69], off offset:256
	s_waitcnt lgkmcnt(0)
	v_mul_f32_e32 v112, v124, v79
	s_waitcnt vmcnt(0)
	v_mul_f32_e32 v101, 0x3f4ccccd, v101
	v_mul_f32_e32 v112, v112, v101
	s_nop 1
	v_mov_b32_dpp v113, v112 quad_perm:[1,0,3,2] row_mask:0xf bank_mask:0xf
	s_and_saveexec_b64 s[8:9], s[6:7]
	s_cbranch_execz .LBB0_241
	s_waitcnt lgkmcnt(0)
	v_cvt_pk_bf16_f32 v112, v112, v113
	global_store_dword v[66:67], v112, off offset:128
.LBB0_241:
	s_or_b64 exec, exec, s[8:9]
	v_mul_f32_e32 v112, v125, v92
	v_mul_f32_e32 v112, v112, v101
	s_waitcnt lgkmcnt(0)
	s_nop 1
	v_mov_b32_dpp v113, v112 quad_perm:[1,0,3,2] row_mask:0xf bank_mask:0xf
	s_and_saveexec_b64 s[8:9], s[6:7]
	s_cbranch_execz .LBB0_243
	s_waitcnt lgkmcnt(0)
	v_cvt_pk_bf16_f32 v124, v112, v113
	v_add_co_u32_e32 v112, vcc, 0x2000, v66
	s_nop 1
	v_addc_co_u32_e32 v113, vcc, 0, v67, vcc
	global_store_dword v[112:113], v124, off offset:128
.LBB0_243:
	s_or_b64 exec, exec, s[8:9]
	v_mul_f32_e32 v112, v120, v93
	v_mul_f32_e32 v112, v112, v101
	s_waitcnt lgkmcnt(0)
	s_nop 1
	v_mov_b32_dpp v113, v112 quad_perm:[1,0,3,2] row_mask:0xf bank_mask:0xf
	s_and_saveexec_b64 s[8:9], s[6:7]
	s_cbranch_execz .LBB0_245
	s_waitcnt lgkmcnt(0)
	v_cvt_pk_bf16_f32 v120, v112, v113
	v_add_co_u32_e32 v112, vcc, 0x4000, v66
	s_nop 1
	v_addc_co_u32_e32 v113, vcc, 0, v67, vcc
	global_store_dword v[112:113], v120, off offset:128
.LBB0_245:
	s_or_b64 exec, exec, s[8:9]
	v_mul_f32_e32 v112, v121, v100
	v_mul_f32_e32 v101, v112, v101
	s_nop 1
	v_mov_b32_dpp v112, v101 quad_perm:[1,0,3,2] row_mask:0xf bank_mask:0xf
	s_and_saveexec_b64 s[8:9], s[6:7]
	s_cbranch_execz .LBB0_247
	s_waitcnt lgkmcnt(0)
	v_cvt_pk_bf16_f32 v101, v101, v112
	v_add_co_u32_e32 v112, vcc, 0x6000, v66
	s_nop 1
	v_addc_co_u32_e32 v113, vcc, 0, v67, vcc
	global_store_dword v[112:113], v101, off offset:128
.LBB0_247:
	s_or_b64 exec, exec, s[8:9]
	global_load_dword v101, v[68:69], off offset:320
	s_waitcnt lgkmcnt(0)
	v_mul_f32_e32 v112, v118, v79
	s_waitcnt vmcnt(0)
	v_mul_f32_e32 v101, 0x3f4ccccd, v101
	v_mul_f32_e32 v112, v112, v101
	s_nop 1
	v_mov_b32_dpp v113, v112 quad_perm:[1,0,3,2] row_mask:0xf bank_mask:0xf
	s_and_saveexec_b64 s[8:9], s[6:7]
	s_cbranch_execz .LBB0_249
	s_waitcnt lgkmcnt(0)
	v_cvt_pk_bf16_f32 v112, v112, v113
	global_store_dword v[66:67], v112, off offset:160
.LBB0_249:
	s_or_b64 exec, exec, s[8:9]
	v_mul_f32_e32 v112, v119, v92
	v_mul_f32_e32 v112, v112, v101
	s_waitcnt lgkmcnt(0)
	s_nop 1
	v_mov_b32_dpp v113, v112 quad_perm:[1,0,3,2] row_mask:0xf bank_mask:0xf
	s_and_saveexec_b64 s[8:9], s[6:7]
	s_cbranch_execz .LBB0_251
	s_waitcnt lgkmcnt(0)
	v_cvt_pk_bf16_f32 v118, v112, v113
	v_add_co_u32_e32 v112, vcc, 0x2000, v66
	s_nop 1
	v_addc_co_u32_e32 v113, vcc, 0, v67, vcc
	global_store_dword v[112:113], v118, off offset:160
.LBB0_251:
	s_or_b64 exec, exec, s[8:9]
	v_mul_f32_e32 v112, v116, v93
	v_mul_f32_e32 v112, v112, v101
	s_waitcnt lgkmcnt(0)
	s_nop 1
	v_mov_b32_dpp v113, v112 quad_perm:[1,0,3,2] row_mask:0xf bank_mask:0xf
	s_and_saveexec_b64 s[8:9], s[6:7]
	s_cbranch_execz .LBB0_253
	s_waitcnt lgkmcnt(0)
	v_cvt_pk_bf16_f32 v116, v112, v113
	v_add_co_u32_e32 v112, vcc, 0x4000, v66
	s_nop 1
	v_addc_co_u32_e32 v113, vcc, 0, v67, vcc
	global_store_dword v[112:113], v116, off offset:160
.LBB0_253:
	s_or_b64 exec, exec, s[8:9]
	v_mul_f32_e32 v112, v117, v100
	v_mul_f32_e32 v101, v112, v101
	s_nop 1
	v_mov_b32_dpp v112, v101 quad_perm:[1,0,3,2] row_mask:0xf bank_mask:0xf
	s_and_saveexec_b64 s[8:9], s[6:7]
	s_cbranch_execz .LBB0_255
	s_waitcnt lgkmcnt(0)
	v_cvt_pk_bf16_f32 v101, v101, v112
	v_add_co_u32_e32 v112, vcc, 0x6000, v66
	s_nop 1
	v_addc_co_u32_e32 v113, vcc, 0, v67, vcc
	global_store_dword v[112:113], v101, off offset:160
.LBB0_255:
	s_or_b64 exec, exec, s[8:9]
	global_load_dword v101, v[68:69], off offset:384
	s_waitcnt lgkmcnt(0)
	v_mul_f32_e32 v112, v114, v79
	s_waitcnt vmcnt(0)
	v_mul_f32_e32 v101, 0x3f4ccccd, v101
	v_mul_f32_e32 v112, v112, v101
	s_nop 1
	v_mov_b32_dpp v113, v112 quad_perm:[1,0,3,2] row_mask:0xf bank_mask:0xf
	s_and_saveexec_b64 s[8:9], s[6:7]
	s_cbranch_execz .LBB0_257
	s_waitcnt lgkmcnt(0)
	v_cvt_pk_bf16_f32 v112, v112, v113
	global_store_dword v[66:67], v112, off offset:192
.LBB0_257:
	s_or_b64 exec, exec, s[8:9]
	v_mul_f32_e32 v112, v115, v92
	v_mul_f32_e32 v112, v112, v101
	s_waitcnt lgkmcnt(0)
	s_nop 1
	v_mov_b32_dpp v113, v112 quad_perm:[1,0,3,2] row_mask:0xf bank_mask:0xf
	s_and_saveexec_b64 s[8:9], s[6:7]
	s_cbranch_execz .LBB0_259
	s_waitcnt lgkmcnt(0)
	v_cvt_pk_bf16_f32 v114, v112, v113
	v_add_co_u32_e32 v112, vcc, 0x2000, v66
	s_nop 1
	v_addc_co_u32_e32 v113, vcc, 0, v67, vcc
	global_store_dword v[112:113], v114, off offset:192
.LBB0_259:
	s_or_b64 exec, exec, s[8:9]
	v_mul_f32_e32 v112, v122, v93
	v_mul_f32_e32 v112, v112, v101
	s_waitcnt lgkmcnt(0)
	s_nop 1
	v_mov_b32_dpp v113, v112 quad_perm:[1,0,3,2] row_mask:0xf bank_mask:0xf
	s_and_saveexec_b64 s[8:9], s[6:7]
	s_cbranch_execz .LBB0_261
	s_waitcnt lgkmcnt(0)
	v_cvt_pk_bf16_f32 v114, v112, v113
	v_add_co_u32_e32 v112, vcc, 0x4000, v66
	s_nop 1
	v_addc_co_u32_e32 v113, vcc, 0, v67, vcc
	global_store_dword v[112:113], v114, off offset:192
.LBB0_261:
	s_or_b64 exec, exec, s[8:9]
	v_mul_f32_e32 v112, v123, v100
	v_mul_f32_e32 v101, v112, v101
	s_nop 1
	v_mov_b32_dpp v112, v101 quad_perm:[1,0,3,2] row_mask:0xf bank_mask:0xf
	s_and_saveexec_b64 s[8:9], s[6:7]
	s_cbranch_execz .LBB0_263
	s_waitcnt lgkmcnt(0)
	v_cvt_pk_bf16_f32 v101, v101, v112
	v_add_co_u32_e32 v112, vcc, 0x6000, v66
	s_nop 1
	v_addc_co_u32_e32 v113, vcc, 0, v67, vcc
	global_store_dword v[112:113], v101, off offset:192
.LBB0_263:
	s_or_b64 exec, exec, s[8:9]
	global_load_dword v101, v[68:69], off offset:448
	v_mul_f32_e32 v106, v106, v79
	s_waitcnt vmcnt(0)
	v_mul_f32_e32 v101, 0x3f4ccccd, v101
	v_mul_f32_e32 v106, v106, v101
	s_waitcnt lgkmcnt(0)
	s_nop 1
	v_mov_b32_dpp v112, v106 quad_perm:[1,0,3,2] row_mask:0xf bank_mask:0xf
	s_and_saveexec_b64 s[8:9], s[6:7]
	s_cbranch_execz .LBB0_265
	s_waitcnt lgkmcnt(0)
	v_cvt_pk_bf16_f32 v106, v106, v112
	global_store_dword v[66:67], v106, off offset:224
.LBB0_265:
	s_or_b64 exec, exec, s[8:9]
	v_mul_f32_e32 v106, v107, v92
	v_mul_f32_e32 v106, v106, v101
	s_nop 1
	v_mov_b32_dpp v107, v106 quad_perm:[1,0,3,2] row_mask:0xf bank_mask:0xf
	s_and_saveexec_b64 s[8:9], s[6:7]
	s_cbranch_execz .LBB0_267
	s_waitcnt lgkmcnt(0)
	v_cvt_pk_bf16_f32 v112, v106, v107
	v_add_co_u32_e32 v106, vcc, 0x2000, v66
	s_nop 1
	v_addc_co_u32_e32 v107, vcc, 0, v67, vcc
	global_store_dword v[106:107], v112, off offset:224
.LBB0_267:
	s_or_b64 exec, exec, s[8:9]
	v_mul_f32_e32 v106, v110, v93
	v_mul_f32_e32 v106, v106, v101
	s_waitcnt lgkmcnt(0)
	s_nop 1
	v_mov_b32_dpp v107, v106 quad_perm:[1,0,3,2] row_mask:0xf bank_mask:0xf
	s_and_saveexec_b64 s[8:9], s[6:7]
	s_cbranch_execz .LBB0_269
	s_waitcnt lgkmcnt(0)
	v_cvt_pk_bf16_f32 v110, v106, v107
	v_add_co_u32_e32 v106, vcc, 0x4000, v66
	s_nop 1
	v_addc_co_u32_e32 v107, vcc, 0, v67, vcc
	global_store_dword v[106:107], v110, off offset:224
.LBB0_269:
	s_or_b64 exec, exec, s[8:9]
	v_mul_f32_e32 v106, v111, v100
	v_mul_f32_e32 v101, v106, v101
	s_nop 1
	v_mov_b32_dpp v106, v101 quad_perm:[1,0,3,2] row_mask:0xf bank_mask:0xf
	s_and_saveexec_b64 s[8:9], s[6:7]
	s_cbranch_execz .LBB0_271
	s_waitcnt lgkmcnt(0)
	v_cvt_pk_bf16_f32 v101, v101, v106
	v_add_co_u32_e32 v106, vcc, 0x6000, v66
	s_nop 1
	v_addc_co_u32_e32 v107, vcc, 0, v67, vcc
	global_store_dword v[106:107], v101, off offset:224
.LBB0_271:
	s_or_b64 exec, exec, s[8:9]
	global_load_dword v101, v[68:69], off offset:512
	v_mul_f32_e32 v102, v102, v79
	s_waitcnt vmcnt(0)
	v_mul_f32_e32 v101, 0x3f4ccccd, v101
	v_mul_f32_e32 v102, v102, v101
	s_waitcnt lgkmcnt(0)
	s_nop 1
	v_mov_b32_dpp v106, v102 quad_perm:[1,0,3,2] row_mask:0xf bank_mask:0xf
	s_and_saveexec_b64 s[8:9], s[6:7]
	s_cbranch_execz .LBB0_273
	s_waitcnt lgkmcnt(0)
	v_cvt_pk_bf16_f32 v102, v102, v106
	global_store_dword v[66:67], v102, off offset:256
.LBB0_273:
	s_or_b64 exec, exec, s[8:9]
	v_mul_f32_e32 v102, v103, v92
	v_mul_f32_e32 v102, v102, v101
	s_nop 1
	v_mov_b32_dpp v103, v102 quad_perm:[1,0,3,2] row_mask:0xf bank_mask:0xf
	s_and_saveexec_b64 s[8:9], s[6:7]
	s_cbranch_execz .LBB0_275
	s_waitcnt lgkmcnt(0)
	v_cvt_pk_bf16_f32 v106, v102, v103
	v_add_co_u32_e32 v102, vcc, 0x2000, v66
	s_nop 1
	v_addc_co_u32_e32 v103, vcc, 0, v67, vcc
	global_store_dword v[102:103], v106, off offset:256
.LBB0_275:
	s_or_b64 exec, exec, s[8:9]
	v_mul_f32_e32 v102, v108, v93
	v_mul_f32_e32 v102, v102, v101
	s_waitcnt lgkmcnt(0)
	s_nop 1
	v_mov_b32_dpp v103, v102 quad_perm:[1,0,3,2] row_mask:0xf bank_mask:0xf
	s_and_saveexec_b64 s[8:9], s[6:7]
	s_cbranch_execz .LBB0_277
	s_waitcnt lgkmcnt(0)
	v_cvt_pk_bf16_f32 v106, v102, v103
	v_add_co_u32_e32 v102, vcc, 0x4000, v66
	s_nop 1
	v_addc_co_u32_e32 v103, vcc, 0, v67, vcc
	global_store_dword v[102:103], v106, off offset:256
.LBB0_277:
	s_or_b64 exec, exec, s[8:9]
	v_mul_f32_e32 v102, v109, v100
	v_mul_f32_e32 v101, v102, v101
	s_nop 1
	v_mov_b32_dpp v102, v101 quad_perm:[1,0,3,2] row_mask:0xf bank_mask:0xf
	s_and_saveexec_b64 s[8:9], s[6:7]
	s_cbranch_execz .LBB0_279
	s_waitcnt lgkmcnt(0)
	v_cvt_pk_bf16_f32 v101, v101, v102
	v_add_co_u32_e32 v102, vcc, 0x6000, v66
	s_nop 1
	v_addc_co_u32_e32 v103, vcc, 0, v67, vcc
	global_store_dword v[102:103], v101, off offset:256
.LBB0_279:
	s_or_b64 exec, exec, s[8:9]
	global_load_dword v101, v[68:69], off offset:576
	v_mul_f32_e32 v96, v96, v79
	s_waitcnt vmcnt(0)
	v_mul_f32_e32 v101, 0x3f4ccccd, v101
	v_mul_f32_e32 v96, v96, v101
	s_waitcnt lgkmcnt(0)
	s_nop 1
	v_mov_b32_dpp v102, v96 quad_perm:[1,0,3,2] row_mask:0xf bank_mask:0xf
	s_and_saveexec_b64 s[8:9], s[6:7]
	s_cbranch_execz .LBB0_281
	s_waitcnt lgkmcnt(0)
	v_cvt_pk_bf16_f32 v96, v96, v102
	global_store_dword v[66:67], v96, off offset:288
.LBB0_281:
	s_or_b64 exec, exec, s[8:9]
	v_mul_f32_e32 v96, v97, v92
	v_mul_f32_e32 v96, v96, v101
	s_nop 1
	v_mov_b32_dpp v97, v96 quad_perm:[1,0,3,2] row_mask:0xf bank_mask:0xf
	s_and_saveexec_b64 s[8:9], s[6:7]
	s_cbranch_execz .LBB0_283
	s_waitcnt lgkmcnt(0)
	v_cvt_pk_bf16_f32 v102, v96, v97
	v_add_co_u32_e32 v96, vcc, 0x2000, v66
	s_nop 1
	v_addc_co_u32_e32 v97, vcc, 0, v67, vcc
	global_store_dword v[96:97], v102, off offset:288
.LBB0_283:
	s_or_b64 exec, exec, s[8:9]
	v_mul_f32_e32 v96, v104, v93
	v_mul_f32_e32 v96, v96, v101
	s_waitcnt lgkmcnt(0)
	s_nop 1
	v_mov_b32_dpp v97, v96 quad_perm:[1,0,3,2] row_mask:0xf bank_mask:0xf
	s_and_saveexec_b64 s[8:9], s[6:7]
	s_cbranch_execz .LBB0_285
	s_waitcnt lgkmcnt(0)
	v_cvt_pk_bf16_f32 v102, v96, v97
	v_add_co_u32_e32 v96, vcc, 0x4000, v66
	s_nop 1
	v_addc_co_u32_e32 v97, vcc, 0, v67, vcc
	global_store_dword v[96:97], v102, off offset:288
.LBB0_285:
	s_or_b64 exec, exec, s[8:9]
	v_mul_f32_e32 v96, v105, v100
	v_mul_f32_e32 v96, v96, v101
	s_waitcnt lgkmcnt(0)
	s_nop 1
	v_mov_b32_dpp v97, v96 quad_perm:[1,0,3,2] row_mask:0xf bank_mask:0xf
	s_and_saveexec_b64 s[8:9], s[6:7]
	s_cbranch_execz .LBB0_287
	s_waitcnt lgkmcnt(0)
	v_cvt_pk_bf16_f32 v101, v96, v97
	v_add_co_u32_e32 v96, vcc, 0x6000, v66
	s_nop 1
	v_addc_co_u32_e32 v97, vcc, 0, v67, vcc
	global_store_dword v[96:97], v101, off offset:288
.LBB0_287:
	s_or_b64 exec, exec, s[8:9]
	global_load_dword v96, v[68:69], off offset:640
	v_mul_f32_e32 v94, v94, v79
	s_waitcnt vmcnt(0)
	v_mul_f32_e32 v96, 0x3f4ccccd, v96
	v_mul_f32_e32 v94, v94, v96
	s_waitcnt lgkmcnt(0)
	s_nop 1
	v_mov_b32_dpp v97, v94 quad_perm:[1,0,3,2] row_mask:0xf bank_mask:0xf
	s_and_saveexec_b64 s[8:9], s[6:7]
	s_cbranch_execz .LBB0_289
	s_waitcnt lgkmcnt(0)
	v_cvt_pk_bf16_f32 v94, v94, v97
	global_store_dword v[66:67], v94, off offset:320
.LBB0_289:
	s_or_b64 exec, exec, s[8:9]
	v_mul_f32_e32 v94, v95, v92
	v_mul_f32_e32 v94, v94, v96
	s_nop 1
	v_mov_b32_dpp v95, v94 quad_perm:[1,0,3,2] row_mask:0xf bank_mask:0xf
	s_and_saveexec_b64 s[8:9], s[6:7]
	s_cbranch_execz .LBB0_291
	s_waitcnt lgkmcnt(0)
	v_cvt_pk_bf16_f32 v97, v94, v95
	v_add_co_u32_e32 v94, vcc, 0x2000, v66
	s_nop 1
	v_addc_co_u32_e32 v95, vcc, 0, v67, vcc
	global_store_dword v[94:95], v97, off offset:320
.LBB0_291:
	s_or_b64 exec, exec, s[8:9]
	v_mul_f32_e32 v94, v98, v93
	v_mul_f32_e32 v94, v94, v96
	s_waitcnt lgkmcnt(0)
	s_nop 1
	v_mov_b32_dpp v95, v94 quad_perm:[1,0,3,2] row_mask:0xf bank_mask:0xf
	s_and_saveexec_b64 s[8:9], s[6:7]
	s_cbranch_execz .LBB0_293
	s_waitcnt lgkmcnt(0)
	v_cvt_pk_bf16_f32 v97, v94, v95
	v_add_co_u32_e32 v94, vcc, 0x4000, v66
	s_nop 1
	v_addc_co_u32_e32 v95, vcc, 0, v67, vcc
	global_store_dword v[94:95], v97, off offset:320
.LBB0_293:
	s_or_b64 exec, exec, s[8:9]
	v_mul_f32_e32 v94, v99, v100
	v_mul_f32_e32 v94, v94, v96
	s_waitcnt lgkmcnt(0)
	s_nop 1
	v_mov_b32_dpp v95, v94 quad_perm:[1,0,3,2] row_mask:0xf bank_mask:0xf
	s_and_saveexec_b64 s[8:9], s[6:7]
	s_cbranch_execz .LBB0_295
	s_waitcnt lgkmcnt(0)
	v_cvt_pk_bf16_f32 v96, v94, v95
	v_add_co_u32_e32 v94, vcc, 0x6000, v66
	s_nop 1
	v_addc_co_u32_e32 v95, vcc, 0, v67, vcc
	global_store_dword v[94:95], v96, off offset:320
.LBB0_295:
	s_or_b64 exec, exec, s[8:9]
	global_load_dword v94, v[68:69], off offset:704
	v_mul_f32_e32 v88, v88, v79
	s_waitcnt vmcnt(0)
	v_mul_f32_e32 v94, 0x3f4ccccd, v94
	v_mul_f32_e32 v88, v88, v94
	s_waitcnt lgkmcnt(0)
	s_nop 1
	v_mov_b32_dpp v95, v88 quad_perm:[1,0,3,2] row_mask:0xf bank_mask:0xf
	s_and_saveexec_b64 s[8:9], s[6:7]
	s_cbranch_execz .LBB0_297
	s_waitcnt lgkmcnt(0)
	v_cvt_pk_bf16_f32 v88, v88, v95
	global_store_dword v[66:67], v88, off offset:352
.LBB0_297:
	s_or_b64 exec, exec, s[8:9]
	v_mul_f32_e32 v88, v89, v92
	v_mul_f32_e32 v88, v88, v94
	s_nop 1
	v_mov_b32_dpp v89, v88 quad_perm:[1,0,3,2] row_mask:0xf bank_mask:0xf
	s_and_saveexec_b64 s[8:9], s[6:7]
	s_cbranch_execz .LBB0_299
	s_waitcnt lgkmcnt(0)
	v_cvt_pk_bf16_f32 v95, v88, v89
	v_add_co_u32_e32 v88, vcc, 0x2000, v66
	s_nop 1
	v_addc_co_u32_e32 v89, vcc, 0, v67, vcc
	global_store_dword v[88:89], v95, off offset:352
.LBB0_299:
	s_or_b64 exec, exec, s[8:9]
	v_mul_f32_e32 v88, v90, v93
	v_mul_f32_e32 v88, v88, v94
	s_waitcnt lgkmcnt(0)
	s_nop 1
	v_mov_b32_dpp v89, v88 quad_perm:[1,0,3,2] row_mask:0xf bank_mask:0xf
	s_and_saveexec_b64 s[8:9], s[6:7]
	s_cbranch_execz .LBB0_301
	s_waitcnt lgkmcnt(0)
	v_cvt_pk_bf16_f32 v90, v88, v89
	v_add_co_u32_e32 v88, vcc, 0x4000, v66
	s_nop 1
	v_addc_co_u32_e32 v89, vcc, 0, v67, vcc
	global_store_dword v[88:89], v90, off offset:352
.LBB0_301:
	s_or_b64 exec, exec, s[8:9]
	v_mul_f32_e32 v88, v91, v100
	v_mul_f32_e32 v88, v88, v94
	s_waitcnt lgkmcnt(0)
	s_nop 1
	v_mov_b32_dpp v89, v88 quad_perm:[1,0,3,2] row_mask:0xf bank_mask:0xf
	s_and_saveexec_b64 s[8:9], s[6:7]
	s_cbranch_execz .LBB0_303
	s_waitcnt lgkmcnt(0)
	v_cvt_pk_bf16_f32 v90, v88, v89
	v_add_co_u32_e32 v88, vcc, 0x6000, v66
	s_nop 1
	v_addc_co_u32_e32 v89, vcc, 0, v67, vcc
	global_store_dword v[88:89], v90, off offset:352
.LBB0_303:
	s_or_b64 exec, exec, s[8:9]
	global_load_dword v88, v[68:69], off offset:768
	v_mul_f32_e32 v86, v86, v79
	s_waitcnt vmcnt(0)
	v_mul_f32_e32 v88, 0x3f4ccccd, v88
	v_mul_f32_e32 v86, v86, v88
	s_waitcnt lgkmcnt(0)
	s_nop 1
	v_mov_b32_dpp v89, v86 quad_perm:[1,0,3,2] row_mask:0xf bank_mask:0xf
	s_and_saveexec_b64 s[8:9], s[6:7]
	s_cbranch_execz .LBB0_305
	s_waitcnt lgkmcnt(0)
	v_cvt_pk_bf16_f32 v86, v86, v89
	global_store_dword v[66:67], v86, off offset:384
.LBB0_305:
	s_or_b64 exec, exec, s[8:9]
	v_mul_f32_e32 v86, v87, v92
	v_mul_f32_e32 v86, v86, v88
	s_nop 1
	v_mov_b32_dpp v87, v86 quad_perm:[1,0,3,2] row_mask:0xf bank_mask:0xf
	s_and_saveexec_b64 s[8:9], s[6:7]
	s_cbranch_execz .LBB0_307
	s_waitcnt lgkmcnt(0)
	v_cvt_pk_bf16_f32 v89, v86, v87
	v_add_co_u32_e32 v86, vcc, 0x2000, v66
	s_nop 1
	v_addc_co_u32_e32 v87, vcc, 0, v67, vcc
	global_store_dword v[86:87], v89, off offset:384
.LBB0_307:
	s_or_b64 exec, exec, s[8:9]
	v_mul_f32_e32 v84, v84, v93
	v_mul_f32_e32 v84, v84, v88
	s_nop 1
	v_mov_b32_dpp v86, v84 quad_perm:[1,0,3,2] row_mask:0xf bank_mask:0xf
	s_and_saveexec_b64 s[8:9], s[6:7]
	s_cbranch_execz .LBB0_309
	s_waitcnt lgkmcnt(0)
	v_cvt_pk_bf16_f32 v84, v84, v86
	v_add_co_u32_e32 v86, vcc, 0x4000, v66
	s_nop 1
	v_addc_co_u32_e32 v87, vcc, 0, v67, vcc
	global_store_dword v[86:87], v84, off offset:384
.LBB0_309:
	s_or_b64 exec, exec, s[8:9]
	v_mul_f32_e32 v84, v85, v100
	v_mul_f32_e32 v84, v84, v88
	s_nop 1
	v_mov_b32_dpp v85, v84 quad_perm:[1,0,3,2] row_mask:0xf bank_mask:0xf
	s_and_saveexec_b64 s[8:9], s[6:7]
	s_cbranch_execz .LBB0_311
	s_waitcnt lgkmcnt(0)
	v_cvt_pk_bf16_f32 v86, v84, v85
	v_add_co_u32_e32 v84, vcc, 0x6000, v66
	s_nop 1
	v_addc_co_u32_e32 v85, vcc, 0, v67, vcc
	global_store_dword v[84:85], v86, off offset:384
.LBB0_311:
	s_or_b64 exec, exec, s[8:9]
	global_load_dword v84, v[68:69], off offset:832
	v_mul_f32_e32 v80, v80, v79
	s_waitcnt vmcnt(0)
	v_mul_f32_e32 v84, 0x3f4ccccd, v84
	v_mul_f32_e32 v80, v80, v84
	s_waitcnt lgkmcnt(0)
	s_nop 1
	v_mov_b32_dpp v85, v80 quad_perm:[1,0,3,2] row_mask:0xf bank_mask:0xf
	s_and_saveexec_b64 s[8:9], s[6:7]
	s_cbranch_execz .LBB0_313
	s_waitcnt lgkmcnt(0)
	v_cvt_pk_bf16_f32 v80, v80, v85
	global_store_dword v[66:67], v80, off offset:416
.LBB0_313:
	s_or_b64 exec, exec, s[8:9]
	v_mul_f32_e32 v80, v81, v92
	v_mul_f32_e32 v80, v80, v84
	s_nop 1
	v_mov_b32_dpp v81, v80 quad_perm:[1,0,3,2] row_mask:0xf bank_mask:0xf
	s_and_saveexec_b64 s[8:9], s[6:7]
	s_cbranch_execz .LBB0_315
	s_waitcnt lgkmcnt(0)
	v_cvt_pk_bf16_f32 v85, v80, v81
	v_add_co_u32_e32 v80, vcc, 0x2000, v66
	s_nop 1
	v_addc_co_u32_e32 v81, vcc, 0, v67, vcc
	global_store_dword v[80:81], v85, off offset:416
.LBB0_315:
	s_or_b64 exec, exec, s[8:9]
	v_mul_f32_e32 v80, v82, v93
	v_mul_f32_e32 v80, v80, v84
	s_waitcnt lgkmcnt(0)
	s_nop 1
	v_mov_b32_dpp v81, v80 quad_perm:[1,0,3,2] row_mask:0xf bank_mask:0xf
	s_and_saveexec_b64 s[8:9], s[6:7]
	s_cbranch_execz .LBB0_317
	s_waitcnt lgkmcnt(0)
	v_cvt_pk_bf16_f32 v82, v80, v81
	v_add_co_u32_e32 v80, vcc, 0x4000, v66
	s_nop 1
	v_addc_co_u32_e32 v81, vcc, 0, v67, vcc
	global_store_dword v[80:81], v82, off offset:416
.LBB0_317:
	s_or_b64 exec, exec, s[8:9]
	v_mul_f32_e32 v80, v83, v100
	v_mul_f32_e32 v80, v80, v84
	s_waitcnt lgkmcnt(0)
	s_nop 1
	v_mov_b32_dpp v81, v80 quad_perm:[1,0,3,2] row_mask:0xf bank_mask:0xf
	s_and_saveexec_b64 s[8:9], s[6:7]
	s_cbranch_execz .LBB0_319
	s_waitcnt lgkmcnt(0)
	v_cvt_pk_bf16_f32 v82, v80, v81
	v_add_co_u32_e32 v80, vcc, 0x6000, v66
	s_nop 1
	v_addc_co_u32_e32 v81, vcc, 0, v67, vcc
	global_store_dword v[80:81], v82, off offset:416
.LBB0_319:
	s_or_b64 exec, exec, s[8:9]
	global_load_dword v80, v[68:69], off offset:896
	v_mul_f32_e32 v74, v74, v79
	s_waitcnt vmcnt(0)
	v_mul_f32_e32 v80, 0x3f4ccccd, v80
	v_mul_f32_e32 v74, v74, v80
	s_waitcnt lgkmcnt(0)
	s_nop 1
	v_mov_b32_dpp v81, v74 quad_perm:[1,0,3,2] row_mask:0xf bank_mask:0xf
	s_and_saveexec_b64 s[8:9], s[6:7]
	s_cbranch_execz .LBB0_321
	s_waitcnt lgkmcnt(0)
	v_cvt_pk_bf16_f32 v74, v74, v81
	global_store_dword v[66:67], v74, off offset:448
.LBB0_321:
	s_or_b64 exec, exec, s[8:9]
	v_mul_f32_e32 v74, v75, v92
	v_mul_f32_e32 v74, v74, v80
	s_nop 1
	v_mov_b32_dpp v75, v74 quad_perm:[1,0,3,2] row_mask:0xf bank_mask:0xf
	s_and_saveexec_b64 s[8:9], s[6:7]
	s_cbranch_execz .LBB0_323
	s_waitcnt lgkmcnt(0)
	v_cvt_pk_bf16_f32 v81, v74, v75
	v_add_co_u32_e32 v74, vcc, 0x2000, v66
	s_nop 1
	v_addc_co_u32_e32 v75, vcc, 0, v67, vcc
	global_store_dword v[74:75], v81, off offset:448
.LBB0_323:
	s_or_b64 exec, exec, s[8:9]
	v_mul_f32_e32 v74, v76, v93
	v_mul_f32_e32 v74, v74, v80
	s_waitcnt lgkmcnt(0)
	s_nop 1
	v_mov_b32_dpp v75, v74 quad_perm:[1,0,3,2] row_mask:0xf bank_mask:0xf
	s_and_saveexec_b64 s[8:9], s[6:7]
	s_cbranch_execz .LBB0_325
	s_waitcnt lgkmcnt(0)
	v_cvt_pk_bf16_f32 v76, v74, v75
	v_add_co_u32_e32 v74, vcc, 0x4000, v66
	s_nop 1
	v_addc_co_u32_e32 v75, vcc, 0, v67, vcc
	global_store_dword v[74:75], v76, off offset:448
.LBB0_325:
	s_or_b64 exec, exec, s[8:9]
	v_mul_f32_e32 v74, v77, v100
	v_mul_f32_e32 v74, v74, v80
	s_waitcnt lgkmcnt(0)
	s_nop 1
	v_mov_b32_dpp v75, v74 quad_perm:[1,0,3,2] row_mask:0xf bank_mask:0xf
	s_and_saveexec_b64 s[8:9], s[6:7]
	s_cbranch_execz .LBB0_327
	s_waitcnt lgkmcnt(0)
	v_cvt_pk_bf16_f32 v76, v74, v75
	v_add_co_u32_e32 v74, vcc, 0x6000, v66
	s_nop 1
	v_addc_co_u32_e32 v75, vcc, 0, v67, vcc
	global_store_dword v[74:75], v76, off offset:448
.LBB0_327:
	s_or_b64 exec, exec, s[8:9]
	global_load_dword v74, v[68:69], off offset:960
	v_mul_f32_e32 v70, v70, v79
	s_waitcnt vmcnt(0)
	v_mul_f32_e32 v74, 0x3f4ccccd, v74
	v_mul_f32_e32 v70, v70, v74
	s_waitcnt lgkmcnt(0)
	s_nop 1
	v_mov_b32_dpp v75, v70 quad_perm:[1,0,3,2] row_mask:0xf bank_mask:0xf
	s_and_saveexec_b64 s[8:9], s[6:7]
	s_cbranch_execz .LBB0_329
	s_waitcnt lgkmcnt(0)
	v_cvt_pk_bf16_f32 v70, v70, v75
	global_store_dword v[66:67], v70, off offset:480
.LBB0_329:
	s_or_b64 exec, exec, s[8:9]
	v_mul_f32_e32 v70, v71, v92
	v_mul_f32_e32 v70, v70, v74
	s_nop 1
	v_mov_b32_dpp v71, v70 quad_perm:[1,0,3,2] row_mask:0xf bank_mask:0xf
	s_and_saveexec_b64 s[8:9], s[6:7]
	s_cbranch_execz .LBB0_331
	s_waitcnt lgkmcnt(0)
	v_cvt_pk_bf16_f32 v75, v70, v71
	v_add_co_u32_e32 v70, vcc, 0x2000, v66
	s_nop 1
	v_addc_co_u32_e32 v71, vcc, 0, v67, vcc
	global_store_dword v[70:71], v75, off offset:480
.LBB0_331:
	s_or_b64 exec, exec, s[8:9]
	v_mul_f32_e32 v70, v72, v93
	v_mul_f32_e32 v70, v70, v74
	s_waitcnt lgkmcnt(0)
	s_nop 1
	v_mov_b32_dpp v71, v70 quad_perm:[1,0,3,2] row_mask:0xf bank_mask:0xf
	s_and_saveexec_b64 s[8:9], s[6:7]
	s_cbranch_execz .LBB0_333
	s_waitcnt lgkmcnt(0)
	v_cvt_pk_bf16_f32 v72, v70, v71
	v_add_co_u32_e32 v70, vcc, 0x4000, v66
	s_nop 1
	v_addc_co_u32_e32 v71, vcc, 0, v67, vcc
	global_store_dword v[70:71], v72, off offset:480
.LBB0_333:
	s_or_b64 exec, exec, s[8:9]
	v_mul_f32_e32 v70, v73, v100
	v_mul_f32_e32 v70, v70, v74
	s_waitcnt lgkmcnt(0)
	s_nop 1
	v_mov_b32_dpp v71, v70 quad_perm:[1,0,3,2] row_mask:0xf bank_mask:0xf
	s_and_saveexec_b64 s[8:9], s[6:7]
	s_cbranch_execz .LBB0_335
	s_waitcnt lgkmcnt(0)
	v_cvt_pk_bf16_f32 v72, v70, v71
	v_add_co_u32_e32 v70, vcc, 0x6000, v66
	s_nop 1
	v_addc_co_u32_e32 v71, vcc, 0, v67, vcc
	global_store_dword v[70:71], v72, off offset:480
.LBB0_335:
	s_or_b64 exec, exec, s[8:9]
	s_waitcnt lgkmcnt(0)
	ds_read_b128 v[70:73], v146 offset:16384
	ds_read_b128 v[84:87], v146 offset:17408
	v_xor_b32_e32 v82, 0x80000000, v78
	v_mov_b32_e32 v79, v78
	v_mov_b32_e32 v83, v82
	s_waitcnt lgkmcnt(0)
	v_pk_fma_f32 v[80:81], v[78:79], v[70:71], v[58:59] neg_lo:[1,0,0] neg_hi:[1,0,0]
	v_pk_fma_f32 v[76:77], v[82:83], v[72:73], v[60:61]
	ds_read_b128 v[58:61], v146 offset:18432
	s_waitcnt lgkmcnt(0)
	v_pk_fma_f32 v[72:73], v[82:83], v[86:87], v[64:65]
	v_pk_fma_f32 v[74:75], v[78:79], v[84:85], v[62:63] neg_lo:[1,0,0] neg_hi:[1,0,0]
	v_pk_mul_f32 v[64:65], v[72:73], v[72:73]
	ds_read_b128 v[84:87], v146 offset:19456
	v_pk_fma_f32 v[88:89], v[76:77], v[76:77], v[64:65]
	s_waitcnt lgkmcnt(0)
	v_pk_fma_f32 v[70:71], v[78:79], v[58:59], v[54:55] neg_lo:[1,0,0] neg_hi:[1,0,0]
	v_pk_fma_f32 v[64:65], v[82:83], v[60:61], v[56:57]
	ds_read_b128 v[54:57], v146 offset:20480
	v_pk_mul_f32 v[62:63], v[74:75], v[74:75]
	v_pk_fma_f32 v[88:89], v[64:65], v[64:65], v[88:89]
	v_pk_fma_f32 v[62:63], v[80:81], v[80:81], v[62:63]
	s_waitcnt lgkmcnt(0)
	v_pk_fma_f32 v[60:61], v[82:83], v[86:87], v[52:53]
	v_pk_fma_f32 v[58:59], v[70:71], v[70:71], v[62:63]
	v_pk_fma_f32 v[62:63], v[78:79], v[84:85], v[50:51] neg_lo:[1,0,0] neg_hi:[1,0,0]
	v_pk_fma_f32 v[84:85], v[60:61], v[60:61], v[88:89]
	v_pk_fma_f32 v[86:87], v[62:63], v[62:63], v[58:59]
	ds_read_b128 v[50:53], v146 offset:21504
	s_waitcnt lgkmcnt(0)
	v_pk_fma_f32 v[58:59], v[78:79], v[54:55], v[46:47] neg_lo:[1,0,0] neg_hi:[1,0,0]
	v_pk_fma_f32 v[56:57], v[82:83], v[56:57], v[48:49]
	v_pk_fma_f32 v[46:47], v[58:59], v[58:59], v[86:87]
	v_pk_fma_f32 v[124:125], v[56:57], v[56:57], v[84:85]
	ds_read_b128 v[84:87], v146 offset:22528
	ds_read_b128 v[88:91], v146 offset:23552
	ds_read_b128 v[92:95], v146 offset:24576
	ds_read_b128 v[96:99], v146 offset:25600
	s_waitcnt lgkmcnt(0)
	v_pk_fma_f32 v[54:55], v[78:79], v[50:51], v[42:43] neg_lo:[1,0,0] neg_hi:[1,0,0]
	ds_read_b128 v[100:103], v146 offset:26624
	ds_read_b128 v[104:107], v146 offset:27648
	v_pk_fma_f32 v[42:43], v[54:55], v[54:55], v[46:47]
	s_waitcnt lgkmcnt(0)
	v_pk_fma_f32 v[50:51], v[78:79], v[84:85], v[2:3] neg_lo:[1,0,0] neg_hi:[1,0,0]
	global_load_dword v84, v[68:69], off
	v_pk_fma_f32 v[2:3], v[50:51], v[50:51], v[42:43]
	s_waitcnt lgkmcnt(0)
	v_pk_fma_f32 v[48:49], v[78:79], v[88:89], v[6:7] neg_lo:[1,0,0] neg_hi:[1,0,0]
	ds_read_b128 v[108:111], v146 offset:28672
	ds_read_b128 v[112:115], v146 offset:29696
	v_pk_fma_f32 v[2:3], v[48:49], v[48:49], v[2:3]
	s_waitcnt lgkmcnt(0)
	v_pk_fma_f32 v[46:47], v[78:79], v[92:93], v[10:11] neg_lo:[1,0,0] neg_hi:[1,0,0]
	v_pk_fma_f32 v[52:53], v[82:83], v[52:53], v[44:45]
	v_pk_fma_f32 v[2:3], v[46:47], v[46:47], v[2:3]
	s_waitcnt lgkmcnt(0)
	v_pk_fma_f32 v[44:45], v[78:79], v[96:97], v[14:15] neg_lo:[1,0,0] neg_hi:[1,0,0]
	ds_read_b128 v[116:119], v146 offset:30720
	ds_read_b128 v[120:123], v146 offset:31744
	v_pk_fma_f32 v[2:3], v[44:45], v[44:45], v[2:3]
	s_waitcnt lgkmcnt(0)
	v_pk_fma_f32 v[42:43], v[78:79], v[100:101], v[18:19] neg_lo:[1,0,0] neg_hi:[1,0,0]
	s_waitcnt lgkmcnt(0)
	v_pk_fma_f32 v[18:19], v[78:79], v[104:105], v[22:23] neg_lo:[1,0,0] neg_hi:[1,0,0]
	v_pk_fma_f32 v[2:3], v[42:43], v[42:43], v[2:3]
	s_waitcnt lgkmcnt(0)
	v_pk_fma_f32 v[14:15], v[78:79], v[108:109], v[34:35] neg_lo:[1,0,0] neg_hi:[1,0,0]
	v_pk_fma_f32 v[2:3], v[18:19], v[18:19], v[2:3]
	s_waitcnt lgkmcnt(0)
	v_pk_fma_f32 v[10:11], v[78:79], v[112:113], v[30:31] neg_lo:[1,0,0] neg_hi:[1,0,0]
	v_pk_fma_f32 v[2:3], v[14:15], v[14:15], v[2:3]
	s_waitcnt lgkmcnt(0)
	v_pk_fma_f32 v[6:7], v[78:79], v[116:117], v[38:39] neg_lo:[1,0,0] neg_hi:[1,0,0]
	v_pk_fma_f32 v[2:3], v[10:11], v[10:11], v[2:3]
	v_pk_fma_f32 v[38:39], v[82:83], v[86:87], v[4:5]
	v_pk_fma_f32 v[22:23], v[6:7], v[6:7], v[2:3]
	s_waitcnt lgkmcnt(0)
	v_pk_fma_f32 v[2:3], v[78:79], v[120:121], v[26:27] neg_lo:[1,0,0] neg_hi:[1,0,0]
	v_pk_fma_f32 v[34:35], v[82:83], v[90:91], v[8:9]
	v_pk_fma_f32 v[78:79], v[2:3], v[2:3], v[22:23]
	s_nop 1
	v_mov_b32_dpp v26, v78 quad_perm:[1,0,3,2] row_mask:0xf bank_mask:0xf
	v_pk_fma_f32 v[22:23], v[52:53], v[52:53], v[124:125]
	v_pk_fma_f32 v[30:31], v[82:83], v[94:95], v[12:13]
	v_pk_fma_f32 v[4:5], v[38:39], v[38:39], v[22:23]
	v_pk_fma_f32 v[12:13], v[82:83], v[114:115], v[32:33]
	s_waitcnt lgkmcnt(0)
	v_add_f32_e32 v22, v78, v26
	s_nop 1
	v_mov_b32_dpp v23, v22 quad_perm:[2,3,0,1] row_mask:0xf bank_mask:0xf
	v_pk_fma_f32 v[4:5], v[34:35], v[34:35], v[4:5]
	v_pk_fma_f32 v[26:27], v[82:83], v[98:99], v[16:17]
	v_pk_fma_f32 v[4:5], v[30:31], v[30:31], v[4:5]
	v_pk_fma_f32 v[16:17], v[82:83], v[110:111], v[36:37]
	s_waitcnt lgkmcnt(0)
	v_add_f32_e32 v8, v22, v23
	s_nop 1
	v_mov_b32_dpp v9, v8 row_half_mirror row_mask:0xf bank_mask:0xf
	v_pk_fma_f32 v[22:23], v[82:83], v[102:103], v[20:21]
	v_pk_fma_f32 v[20:21], v[82:83], v[106:107], v[24:25]
	v_pk_fma_f32 v[4:5], v[26:27], v[26:27], v[4:5]
	s_waitcnt lgkmcnt(0)
	v_add_f32_e32 v8, v8, v9
	s_nop 1
	v_mov_b32_dpp v9, v8 row_mirror row_mask:0xf bank_mask:0xf
	v_pk_fma_f32 v[4:5], v[22:23], v[22:23], v[4:5]
	s_waitcnt lgkmcnt(0)
	v_add_f32_e32 v8, v8, v9
	v_fmamk_f32 v8, v8, 0x3b800000, v1
	v_mul_f32_e32 v9, 0x4f800000, v8
	v_cmp_gt_f32_e32 vcc, s53, v8
	v_pk_fma_f32 v[4:5], v[20:21], v[20:21], v[4:5]
	s_nop 0
	v_cndmask_b32_e32 v24, v8, v9, vcc
	v_sqrt_f32_e32 v25, v24
	v_pk_fma_f32 v[4:5], v[16:17], v[16:17], v[4:5]
	v_pk_fma_f32 v[8:9], v[82:83], v[118:119], v[40:41]
	v_pk_fma_f32 v[4:5], v[12:13], v[12:13], v[4:5]
	v_add_u32_e32 v32, -1, v25
	v_fma_f32 v33, -v32, v25, v24
	v_cmp_ge_f32_e64 s[8:9], 0, v33
	v_add_u32_e32 v33, 1, v25
	s_nop 0
	v_cndmask_b32_e64 v32, v25, v32, s[8:9]
	v_fma_f32 v25, -v33, v25, v24
	v_cmp_lt_f32_e64 s[8:9], 0, v25
	s_nop 1
	v_cndmask_b32_e64 v25, v32, v33, s[8:9]
	v_mul_f32_e32 v32, 0x37800000, v25
	v_cndmask_b32_e32 v25, v25, v32, vcc
	v_cmp_class_f32_e32 vcc, v24, v224
	s_nop 1
	v_cndmask_b32_e32 v32, v25, v24, vcc
	v_div_scale_f32 v33, s[8:9], v32, v32, 1.0
	v_rcp_f32_e32 v36, v33
	v_pk_fma_f32 v[24:25], v[8:9], v[8:9], v[4:5]
	v_pk_fma_f32 v[4:5], v[82:83], v[122:123], v[28:29]
	s_nop 0
	v_pk_fma_f32 v[28:29], v[4:5], v[4:5], v[24:25]
	v_fma_f32 v24, -v33, v36, 1.0
	v_fmac_f32_e32 v36, v24, v36
	v_div_scale_f32 v24, vcc, 1.0, v32, 1.0
	v_mul_f32_e32 v25, v24, v36
	v_fma_f32 v37, -v33, v25, v24
	v_fmac_f32_e32 v25, v37, v36
	v_fma_f32 v24, -v33, v25, v24
	v_div_fmas_f32 v24, v24, v36, v25
	s_nop 1
	v_mov_b32_dpp v25, v28 quad_perm:[1,0,3,2] row_mask:0xf bank_mask:0xf
	v_div_fixup_f32 v24, v24, v32, 1.0
	s_nop 1
	v_mov_b32_dpp v32, v29 quad_perm:[1,0,3,2] row_mask:0xf bank_mask:0xf
	s_nop 1
	v_mov_b32_dpp v33, v79 quad_perm:[1,0,3,2] row_mask:0xf bank_mask:0xf
	s_waitcnt lgkmcnt(0)
	v_add_f32_e32 v25, v28, v25
	s_nop 1
	v_mov_b32_dpp v28, v25 quad_perm:[2,3,0,1] row_mask:0xf bank_mask:0xf
	s_waitcnt lgkmcnt(0)
	v_add_f32_e32 v29, v29, v32
	s_waitcnt lgkmcnt(0)
	v_add_f32_e32 v33, v79, v33
	s_nop 1
	v_mov_b32_dpp v32, v29 quad_perm:[2,3,0,1] row_mask:0xf bank_mask:0xf
	s_nop 1
	v_mov_b32_dpp v36, v33 quad_perm:[2,3,0,1] row_mask:0xf bank_mask:0xf
	s_waitcnt lgkmcnt(0)
	v_add_f32_e32 v28, v25, v28
	s_nop 1
	v_mov_b32_dpp v40, v28 row_half_mirror row_mask:0xf bank_mask:0xf
	s_waitcnt lgkmcnt(0)
	v_add_f32_e32 v29, v29, v32
	s_waitcnt lgkmcnt(0)
	v_add_f32_e32 v33, v33, v36
	s_nop 1
	v_mov_b32_dpp v32, v29 row_half_mirror row_mask:0xf bank_mask:0xf
	s_nop 1
	v_mov_b32_dpp v36, v33 row_half_mirror row_mask:0xf bank_mask:0xf
	s_waitcnt lgkmcnt(0)
	v_add_f32_e32 v28, v28, v40
	v_mul_f32_e32 v40, v80, v24
	s_waitcnt lgkmcnt(0)
	v_add_f32_e32 v29, v29, v32
	s_waitcnt vmcnt(0)
	v_mul_f32_e32 v32, 0x3f4ccccd, v84
	s_waitcnt lgkmcnt(0)
	v_add_f32_e32 v25, v33, v36
	v_mul_f32_e32 v40, v40, v32
	s_nop 1
	v_mov_b32_dpp v37, v25 row_mirror row_mask:0xf bank_mask:0xf
	s_nop 1
	v_mov_b32_dpp v36, v28 row_mirror row_mask:0xf bank_mask:0xf
	s_nop 1
	v_mov_b32_dpp v33, v29 row_mirror row_mask:0xf bank_mask:0xf
	s_nop 1
	v_mov_b32_dpp v41, v40 quad_perm:[1,0,3,2] row_mask:0xf bank_mask:0xf
	s_and_saveexec_b64 s[8:9], s[6:7]
	s_cbranch_execz .LBB0_337
	s_waitcnt lgkmcnt(0)
	v_cvt_pk_bf16_f32 v78, v40, v41
	v_add_co_u32_e32 v40, vcc, 0x20000, v66
	s_nop 1
	v_addc_co_u32_e32 v41, vcc, 0, v67, vcc
	global_store_dword v[40:41], v78, off
.LBB0_337:
	s_or_b64 exec, exec, s[8:9]
	s_waitcnt lgkmcnt(0)
	v_add_f32_e32 v25, v25, v37
	v_fmamk_f32 v25, v25, 0x3b800000, v1
	v_mul_f32_e32 v37, 0x4f800000, v25
	v_cmp_gt_f32_e32 vcc, s53, v25
	s_nop 1
	v_cndmask_b32_e32 v25, v25, v37, vcc
	v_sqrt_f32_e32 v37, v25
	s_nop 0
	v_add_u32_e32 v40, -1, v37
	v_fma_f32 v78, -v40, v37, v25
	s_waitcnt lgkmcnt(0)
	v_add_u32_e32 v41, 1, v37
	v_cmp_ge_f32_e64 s[8:9], 0, v78
	s_nop 1
	v_cndmask_b32_e64 v40, v37, v40, s[8:9]
	v_fma_f32 v37, -v41, v37, v25
	v_cmp_lt_f32_e64 s[8:9], 0, v37
	s_nop 1
	v_cndmask_b32_e64 v37, v40, v41, s[8:9]
	v_mul_f32_e32 v40, 0x37800000, v37
	v_cndmask_b32_e32 v37, v37, v40, vcc
	v_cmp_class_f32_e32 vcc, v25, v224
	s_nop 1
	v_cndmask_b32_e32 v25, v37, v25, vcc
	v_div_scale_f32 v37, s[8:9], v25, v25, 1.0
	v_rcp_f32_e32 v40, v37
	s_nop 0
	v_fma_f32 v41, -v37, v40, 1.0
	v_fmac_f32_e32 v40, v41, v40
	v_div_scale_f32 v41, vcc, 1.0, v25, 1.0
	v_mul_f32_e32 v78, v41, v40
	v_fma_f32 v79, -v37, v78, v41
	v_fmac_f32_e32 v78, v79, v40
	v_fma_f32 v37, -v37, v78, v41
	v_div_fmas_f32 v37, v37, v40, v78
	v_div_fixup_f32 v25, v37, v25, 1.0
	v_mul_f32_e32 v37, v81, v25
	v_mul_f32_e32 v37, v37, v32
	s_nop 1
	v_mov_b32_dpp v40, v37 quad_perm:[1,0,3,2] row_mask:0xf bank_mask:0xf
	s_and_saveexec_b64 s[8:9], s[6:7]
	s_cbranch_execz .LBB0_339
	s_waitcnt lgkmcnt(0)
	v_cvt_pk_bf16_f32 v37, v37, v40
	v_add_co_u32_e32 v40, vcc, 0x22000, v66
	s_nop 1
	v_addc_co_u32_e32 v41, vcc, 0, v67, vcc
	global_store_dword v[40:41], v37, off
.LBB0_339:
	s_or_b64 exec, exec, s[8:9]
	v_add_f32_e32 v28, v28, v36
	v_fmamk_f32 v28, v28, 0x3b800000, v1
	v_mul_f32_e32 v36, 0x4f800000, v28
	v_cmp_gt_f32_e32 vcc, s53, v28
	s_nop 1
	v_cndmask_b32_e32 v28, v28, v36, vcc
	v_sqrt_f32_e32 v36, v28
	s_nop 0
	v_add_u32_e32 v37, -1, v36
	v_fma_f32 v41, -v37, v36, v28
	s_waitcnt lgkmcnt(0)
	v_add_u32_e32 v40, 1, v36
	v_cmp_ge_f32_e64 s[8:9], 0, v41
	s_nop 1
	v_cndmask_b32_e64 v37, v36, v37, s[8:9]
	v_fma_f32 v36, -v40, v36, v28
	v_cmp_lt_f32_e64 s[8:9], 0, v36
	s_nop 1
	v_cndmask_b32_e64 v36, v37, v40, s[8:9]
	v_mul_f32_e32 v37, 0x37800000, v36
	v_cndmask_b32_e32 v36, v36, v37, vcc
	v_cmp_class_f32_e32 vcc, v28, v224
	s_nop 1
	v_cndmask_b32_e32 v28, v36, v28, vcc
	v_div_scale_f32 v36, s[8:9], v28, v28, 1.0
	v_rcp_f32_e32 v37, v36
	s_nop 0
	v_fma_f32 v40, -v36, v37, 1.0
	v_fmac_f32_e32 v37, v40, v37
	v_div_scale_f32 v40, vcc, 1.0, v28, 1.0
	v_mul_f32_e32 v41, v40, v37
	v_fma_f32 v78, -v36, v41, v40
	v_fmac_f32_e32 v41, v78, v37
	v_fma_f32 v36, -v36, v41, v40
	v_div_fmas_f32 v36, v36, v37, v41
	v_div_fixup_f32 v28, v36, v28, 1.0
	v_mul_f32_e32 v36, v76, v28
	v_mul_f32_e32 v36, v32, v36
	s_nop 1
	v_mov_b32_dpp v37, v36 quad_perm:[1,0,3,2] row_mask:0xf bank_mask:0xf
	s_and_saveexec_b64 s[8:9], s[6:7]
	s_cbranch_execz .LBB0_341
	s_waitcnt lgkmcnt(0)
	v_cvt_pk_bf16_f32 v40, v36, v37
	v_add_co_u32_e32 v36, vcc, 0x24000, v66
	s_nop 1
	v_addc_co_u32_e32 v37, vcc, 0, v67, vcc
	global_store_dword v[36:37], v40, off
.LBB0_341:
	s_or_b64 exec, exec, s[8:9]
	v_add_f32_e32 v29, v29, v33
	v_fmamk_f32 v29, v29, 0x3b800000, v1
	v_mul_f32_e32 v33, 0x4f800000, v29
	v_cmp_gt_f32_e32 vcc, s53, v29
	s_nop 1
	v_cndmask_b32_e32 v29, v29, v33, vcc
	v_sqrt_f32_e32 v33, v29
	s_nop 0
	v_add_u32_e32 v36, -1, v33
	v_fma_f32 v40, -v36, v33, v29
	s_waitcnt lgkmcnt(0)
	v_add_u32_e32 v37, 1, v33
	v_cmp_ge_f32_e64 s[8:9], 0, v40
	s_nop 1
	v_cndmask_b32_e64 v36, v33, v36, s[8:9]
	v_fma_f32 v33, -v37, v33, v29
	v_cmp_lt_f32_e64 s[8:9], 0, v33
	s_nop 1
	v_cndmask_b32_e64 v33, v36, v37, s[8:9]
	v_mul_f32_e32 v36, 0x37800000, v33
	v_cndmask_b32_e32 v33, v33, v36, vcc
	v_cmp_class_f32_e32 vcc, v29, v224
	s_nop 1
	v_cndmask_b32_e32 v29, v33, v29, vcc
	v_div_scale_f32 v33, s[8:9], v29, v29, 1.0
	v_rcp_f32_e32 v36, v33
	s_nop 0
	v_fma_f32 v37, -v33, v36, 1.0
	v_fmac_f32_e32 v36, v37, v36
	v_div_scale_f32 v37, vcc, 1.0, v29, 1.0
	v_mul_f32_e32 v40, v37, v36
	v_fma_f32 v41, -v33, v40, v37
	v_fmac_f32_e32 v40, v41, v36
	v_fma_f32 v33, -v33, v40, v37
	v_div_fmas_f32 v33, v33, v36, v40
	v_div_fixup_f32 v29, v33, v29, 1.0
	v_mul_f32_e32 v33, v77, v29
	v_mul_f32_e32 v32, v32, v33
	s_nop 1
	v_mov_b32_dpp v33, v32 quad_perm:[1,0,3,2] row_mask:0xf bank_mask:0xf
	s_and_saveexec_b64 s[8:9], s[6:7]
	s_cbranch_execz .LBB0_343
	s_waitcnt lgkmcnt(0)
	v_cvt_pk_bf16_f32 v36, v32, v33
	v_add_co_u32_e32 v32, vcc, 0x26000, v66
	s_nop 1
	v_addc_co_u32_e32 v33, vcc, 0, v67, vcc
	global_store_dword v[32:33], v36, off
.LBB0_343:
	s_or_b64 exec, exec, s[8:9]
	global_load_dword v32, v[68:69], off offset:64
	s_waitcnt lgkmcnt(0)
	v_mul_f32_e32 v33, v74, v24
	s_waitcnt vmcnt(0)
	v_mul_f32_e32 v32, 0x3f4ccccd, v32
	v_mul_f32_e32 v33, v33, v32
	s_nop 1
	v_mov_b32_dpp v36, v33 quad_perm:[1,0,3,2] row_mask:0xf bank_mask:0xf
	s_and_saveexec_b64 s[8:9], s[6:7]
	s_cbranch_execz .LBB0_345
	s_waitcnt lgkmcnt(0)
	v_cvt_pk_bf16_f32 v33, v33, v36
	v_add_co_u32_e32 v36, vcc, 0x20000, v66
	s_nop 1
	v_addc_co_u32_e32 v37, vcc, 0, v67, vcc
	global_store_dword v[36:37], v33, off offset:32
.LBB0_345:
	s_or_b64 exec, exec, s[8:9]
	v_mul_f32_e32 v33, v75, v25
	v_mul_f32_e32 v33, v33, v32
	s_waitcnt lgkmcnt(0)
	s_nop 1
	v_mov_b32_dpp v36, v33 quad_perm:[1,0,3,2] row_mask:0xf bank_mask:0xf
	s_and_saveexec_b64 s[8:9], s[6:7]
	s_cbranch_execz .LBB0_347
	s_waitcnt lgkmcnt(0)
	v_cvt_pk_bf16_f32 v33, v33, v36
	v_add_co_u32_e32 v36, vcc, 0x22000, v66
	s_nop 1
	v_addc_co_u32_e32 v37, vcc, 0, v67, vcc
	global_store_dword v[36:37], v33, off offset:32
.LBB0_347:
	s_or_b64 exec, exec, s[8:9]
	v_mul_f32_e32 v33, v72, v28
	v_mul_f32_e32 v33, v33, v32
	s_waitcnt lgkmcnt(0)
	s_nop 1
	v_mov_b32_dpp v36, v33 quad_perm:[1,0,3,2] row_mask:0xf bank_mask:0xf
	s_and_saveexec_b64 s[8:9], s[6:7]
	s_cbranch_execz .LBB0_349
	s_waitcnt lgkmcnt(0)
	v_cvt_pk_bf16_f32 v33, v33, v36
	v_add_co_u32_e32 v36, vcc, 0x24000, v66
	s_nop 1
	v_addc_co_u32_e32 v37, vcc, 0, v67, vcc
	global_store_dword v[36:37], v33, off offset:32
.LBB0_349:
	s_or_b64 exec, exec, s[8:9]
	v_mul_f32_e32 v33, v73, v29
	v_mul_f32_e32 v32, v33, v32
	s_nop 1
	v_mov_b32_dpp v33, v32 quad_perm:[1,0,3,2] row_mask:0xf bank_mask:0xf
	s_and_saveexec_b64 s[8:9], s[6:7]
	s_cbranch_execz .LBB0_351
	s_waitcnt lgkmcnt(0)
	v_cvt_pk_bf16_f32 v36, v32, v33
	v_add_co_u32_e32 v32, vcc, 0x26000, v66
	s_nop 1
	v_addc_co_u32_e32 v33, vcc, 0, v67, vcc
	global_store_dword v[32:33], v36, off offset:32
.LBB0_351:
	s_or_b64 exec, exec, s[8:9]
	global_load_dword v32, v[68:69], off offset:128
	s_waitcnt lgkmcnt(0)
	v_mul_f32_e32 v33, v70, v24
	s_waitcnt vmcnt(0)
	v_mul_f32_e32 v32, 0x3f4ccccd, v32
	v_mul_f32_e32 v33, v33, v32
	s_nop 1
	v_mov_b32_dpp v36, v33 quad_perm:[1,0,3,2] row_mask:0xf bank_mask:0xf
	s_and_saveexec_b64 s[8:9], s[6:7]
	s_cbranch_execz .LBB0_353
	s_waitcnt lgkmcnt(0)
	v_cvt_pk_bf16_f32 v33, v33, v36
	v_add_co_u32_e32 v36, vcc, 0x20000, v66
	s_nop 1
	v_addc_co_u32_e32 v37, vcc, 0, v67, vcc
	global_store_dword v[36:37], v33, off offset:64
.LBB0_353:
	s_or_b64 exec, exec, s[8:9]
	v_mul_f32_e32 v33, v71, v25
	v_mul_f32_e32 v33, v33, v32
	s_waitcnt lgkmcnt(0)
	s_nop 1
	v_mov_b32_dpp v36, v33 quad_perm:[1,0,3,2] row_mask:0xf bank_mask:0xf
	s_and_saveexec_b64 s[8:9], s[6:7]
	s_cbranch_execz .LBB0_355
	s_waitcnt lgkmcnt(0)
	v_cvt_pk_bf16_f32 v33, v33, v36
	v_add_co_u32_e32 v36, vcc, 0x22000, v66
	s_nop 1
	v_addc_co_u32_e32 v37, vcc, 0, v67, vcc
	global_store_dword v[36:37], v33, off offset:64
.LBB0_355:
	s_or_b64 exec, exec, s[8:9]
	v_mul_f32_e32 v33, v64, v28
	v_mul_f32_e32 v33, v33, v32
	s_waitcnt lgkmcnt(0)
	s_nop 1
	v_mov_b32_dpp v36, v33 quad_perm:[1,0,3,2] row_mask:0xf bank_mask:0xf
	s_and_saveexec_b64 s[8:9], s[6:7]
	s_cbranch_execz .LBB0_357
	s_waitcnt lgkmcnt(0)
	v_cvt_pk_bf16_f32 v33, v33, v36
	v_add_co_u32_e32 v36, vcc, 0x24000, v66
	s_nop 1
	v_addc_co_u32_e32 v37, vcc, 0, v67, vcc
	global_store_dword v[36:37], v33, off offset:64
.LBB0_357:
	s_or_b64 exec, exec, s[8:9]
	v_mul_f32_e32 v33, v65, v29
	v_mul_f32_e32 v32, v33, v32
	s_nop 1
	v_mov_b32_dpp v33, v32 quad_perm:[1,0,3,2] row_mask:0xf bank_mask:0xf
	s_and_saveexec_b64 s[8:9], s[6:7]
	s_cbranch_execz .LBB0_359
	s_waitcnt lgkmcnt(0)
	v_cvt_pk_bf16_f32 v36, v32, v33
	v_add_co_u32_e32 v32, vcc, 0x26000, v66
	s_nop 1
	v_addc_co_u32_e32 v33, vcc, 0, v67, vcc
	global_store_dword v[32:33], v36, off offset:64
.LBB0_359:
	s_or_b64 exec, exec, s[8:9]
	global_load_dword v32, v[68:69], off offset:192
	s_waitcnt lgkmcnt(0)
	v_mul_f32_e32 v33, v62, v24
	s_waitcnt vmcnt(0)
	v_mul_f32_e32 v32, 0x3f4ccccd, v32
	v_mul_f32_e32 v33, v33, v32
	s_nop 1
	v_mov_b32_dpp v36, v33 quad_perm:[1,0,3,2] row_mask:0xf bank_mask:0xf
	s_and_saveexec_b64 s[8:9], s[6:7]
	s_cbranch_execz .LBB0_361
	s_waitcnt lgkmcnt(0)
	v_cvt_pk_bf16_f32 v33, v33, v36
	v_add_co_u32_e32 v36, vcc, 0x20000, v66
	s_nop 1
	v_addc_co_u32_e32 v37, vcc, 0, v67, vcc
	global_store_dword v[36:37], v33, off offset:96
.LBB0_361:
	s_or_b64 exec, exec, s[8:9]
	v_mul_f32_e32 v33, v63, v25
	v_mul_f32_e32 v33, v33, v32
	s_waitcnt lgkmcnt(0)
	s_nop 1
	v_mov_b32_dpp v36, v33 quad_perm:[1,0,3,2] row_mask:0xf bank_mask:0xf
	s_and_saveexec_b64 s[8:9], s[6:7]
	s_cbranch_execz .LBB0_363
	s_waitcnt lgkmcnt(0)
	v_cvt_pk_bf16_f32 v33, v33, v36
	v_add_co_u32_e32 v36, vcc, 0x22000, v66
	s_nop 1
	v_addc_co_u32_e32 v37, vcc, 0, v67, vcc
	global_store_dword v[36:37], v33, off offset:96
.LBB0_363:
	s_or_b64 exec, exec, s[8:9]
	v_mul_f32_e32 v33, v60, v28
	v_mul_f32_e32 v33, v33, v32
	s_waitcnt lgkmcnt(0)
	s_nop 1
	v_mov_b32_dpp v36, v33 quad_perm:[1,0,3,2] row_mask:0xf bank_mask:0xf
	s_and_saveexec_b64 s[8:9], s[6:7]
	s_cbranch_execz .LBB0_365
	s_waitcnt lgkmcnt(0)
	v_cvt_pk_bf16_f32 v33, v33, v36
	v_add_co_u32_e32 v36, vcc, 0x24000, v66
	s_nop 1
	v_addc_co_u32_e32 v37, vcc, 0, v67, vcc
	global_store_dword v[36:37], v33, off offset:96
.LBB0_365:
	s_or_b64 exec, exec, s[8:9]
	v_mul_f32_e32 v33, v61, v29
	v_mul_f32_e32 v32, v33, v32
	s_nop 1
	v_mov_b32_dpp v33, v32 quad_perm:[1,0,3,2] row_mask:0xf bank_mask:0xf
	s_and_saveexec_b64 s[8:9], s[6:7]
	s_cbranch_execz .LBB0_367
	s_waitcnt lgkmcnt(0)
	v_cvt_pk_bf16_f32 v36, v32, v33
	v_add_co_u32_e32 v32, vcc, 0x26000, v66
	s_nop 1
	v_addc_co_u32_e32 v33, vcc, 0, v67, vcc
	global_store_dword v[32:33], v36, off offset:96
.LBB0_367:
	s_or_b64 exec, exec, s[8:9]
	global_load_dword v32, v[68:69], off offset:256
	s_waitcnt lgkmcnt(0)
	v_mul_f32_e32 v33, v58, v24
	s_waitcnt vmcnt(0)
	v_mul_f32_e32 v32, 0x3f4ccccd, v32
	v_mul_f32_e32 v33, v33, v32
	s_nop 1
	v_mov_b32_dpp v36, v33 quad_perm:[1,0,3,2] row_mask:0xf bank_mask:0xf
	s_and_saveexec_b64 s[8:9], s[6:7]
	s_cbranch_execz .LBB0_369
	s_waitcnt lgkmcnt(0)
	v_cvt_pk_bf16_f32 v33, v33, v36
	v_add_co_u32_e32 v36, vcc, 0x20000, v66
	s_nop 1
	v_addc_co_u32_e32 v37, vcc, 0, v67, vcc
	global_store_dword v[36:37], v33, off offset:128
.LBB0_369:
	s_or_b64 exec, exec, s[8:9]
	v_mul_f32_e32 v33, v59, v25
	v_mul_f32_e32 v33, v33, v32
	s_waitcnt lgkmcnt(0)
	s_nop 1
	v_mov_b32_dpp v36, v33 quad_perm:[1,0,3,2] row_mask:0xf bank_mask:0xf
	s_and_saveexec_b64 s[8:9], s[6:7]
	s_cbranch_execz .LBB0_371
	s_waitcnt lgkmcnt(0)
	v_cvt_pk_bf16_f32 v33, v33, v36
	v_add_co_u32_e32 v36, vcc, 0x22000, v66
	s_nop 1
	v_addc_co_u32_e32 v37, vcc, 0, v67, vcc
	global_store_dword v[36:37], v33, off offset:128
.LBB0_371:
	s_or_b64 exec, exec, s[8:9]
	v_mul_f32_e32 v33, v56, v28
	v_mul_f32_e32 v33, v33, v32
	s_waitcnt lgkmcnt(0)
	s_nop 1
	v_mov_b32_dpp v36, v33 quad_perm:[1,0,3,2] row_mask:0xf bank_mask:0xf
	s_and_saveexec_b64 s[8:9], s[6:7]
	s_cbranch_execz .LBB0_373
	s_waitcnt lgkmcnt(0)
	v_cvt_pk_bf16_f32 v33, v33, v36
	v_add_co_u32_e32 v36, vcc, 0x24000, v66
	s_nop 1
	v_addc_co_u32_e32 v37, vcc, 0, v67, vcc
	global_store_dword v[36:37], v33, off offset:128
.LBB0_373:
	s_or_b64 exec, exec, s[8:9]
	v_mul_f32_e32 v33, v57, v29
	v_mul_f32_e32 v32, v33, v32
	s_nop 1
	v_mov_b32_dpp v33, v32 quad_perm:[1,0,3,2] row_mask:0xf bank_mask:0xf
	s_and_saveexec_b64 s[8:9], s[6:7]
	s_cbranch_execz .LBB0_375
	s_waitcnt lgkmcnt(0)
	v_cvt_pk_bf16_f32 v36, v32, v33
	v_add_co_u32_e32 v32, vcc, 0x26000, v66
	s_nop 1
	v_addc_co_u32_e32 v33, vcc, 0, v67, vcc
	global_store_dword v[32:33], v36, off offset:128
.LBB0_375:
	s_or_b64 exec, exec, s[8:9]
	global_load_dword v32, v[68:69], off offset:320
	s_waitcnt lgkmcnt(0)
	v_mul_f32_e32 v33, v54, v24
	s_waitcnt vmcnt(0)
	v_mul_f32_e32 v32, 0x3f4ccccd, v32
	v_mul_f32_e32 v33, v33, v32
	s_nop 1
	v_mov_b32_dpp v36, v33 quad_perm:[1,0,3,2] row_mask:0xf bank_mask:0xf
	s_and_saveexec_b64 s[8:9], s[6:7]
	s_cbranch_execz .LBB0_377
	s_waitcnt lgkmcnt(0)
	v_cvt_pk_bf16_f32 v33, v33, v36
	v_add_co_u32_e32 v36, vcc, 0x20000, v66
	s_nop 1
	v_addc_co_u32_e32 v37, vcc, 0, v67, vcc
	global_store_dword v[36:37], v33, off offset:160
.LBB0_377:
	s_or_b64 exec, exec, s[8:9]
	v_mul_f32_e32 v33, v55, v25
	v_mul_f32_e32 v33, v33, v32
	s_waitcnt lgkmcnt(0)
	s_nop 1
	v_mov_b32_dpp v36, v33 quad_perm:[1,0,3,2] row_mask:0xf bank_mask:0xf
	s_and_saveexec_b64 s[8:9], s[6:7]
	s_cbranch_execz .LBB0_379
	s_waitcnt lgkmcnt(0)
	v_cvt_pk_bf16_f32 v33, v33, v36
	v_add_co_u32_e32 v36, vcc, 0x22000, v66
	s_nop 1
	v_addc_co_u32_e32 v37, vcc, 0, v67, vcc
	global_store_dword v[36:37], v33, off offset:160
.LBB0_379:
	s_or_b64 exec, exec, s[8:9]
	v_mul_f32_e32 v33, v52, v28
	v_mul_f32_e32 v33, v33, v32
	s_waitcnt lgkmcnt(0)
	s_nop 1
	v_mov_b32_dpp v36, v33 quad_perm:[1,0,3,2] row_mask:0xf bank_mask:0xf
	s_and_saveexec_b64 s[8:9], s[6:7]
	s_cbranch_execz .LBB0_381
	s_waitcnt lgkmcnt(0)
	v_cvt_pk_bf16_f32 v33, v33, v36
	v_add_co_u32_e32 v36, vcc, 0x24000, v66
	s_nop 1
	v_addc_co_u32_e32 v37, vcc, 0, v67, vcc
	global_store_dword v[36:37], v33, off offset:160
.LBB0_381:
	s_or_b64 exec, exec, s[8:9]
	v_mul_f32_e32 v33, v53, v29
	v_mul_f32_e32 v32, v33, v32
	s_nop 1
	v_mov_b32_dpp v33, v32 quad_perm:[1,0,3,2] row_mask:0xf bank_mask:0xf
	s_and_saveexec_b64 s[8:9], s[6:7]
	s_cbranch_execz .LBB0_383
	s_waitcnt lgkmcnt(0)
	v_cvt_pk_bf16_f32 v36, v32, v33
	v_add_co_u32_e32 v32, vcc, 0x26000, v66
	s_nop 1
	v_addc_co_u32_e32 v33, vcc, 0, v67, vcc
	global_store_dword v[32:33], v36, off offset:160
.LBB0_383:
	s_or_b64 exec, exec, s[8:9]
	global_load_dword v32, v[68:69], off offset:384
	s_waitcnt lgkmcnt(0)
	v_mul_f32_e32 v33, v50, v24
	s_waitcnt vmcnt(0)
	v_mul_f32_e32 v32, 0x3f4ccccd, v32
	v_mul_f32_e32 v33, v33, v32
	s_nop 1
	v_mov_b32_dpp v36, v33 quad_perm:[1,0,3,2] row_mask:0xf bank_mask:0xf
	s_and_saveexec_b64 s[8:9], s[6:7]
	s_cbranch_execz .LBB0_385
	s_waitcnt lgkmcnt(0)
	v_cvt_pk_bf16_f32 v33, v33, v36
	v_add_co_u32_e32 v36, vcc, 0x20000, v66
	s_nop 1
	v_addc_co_u32_e32 v37, vcc, 0, v67, vcc
	global_store_dword v[36:37], v33, off offset:192
.LBB0_385:
	s_or_b64 exec, exec, s[8:9]
	v_mul_f32_e32 v33, v51, v25
	v_mul_f32_e32 v33, v33, v32
	s_waitcnt lgkmcnt(0)
	s_nop 1
	v_mov_b32_dpp v36, v33 quad_perm:[1,0,3,2] row_mask:0xf bank_mask:0xf
	s_and_saveexec_b64 s[8:9], s[6:7]
	s_cbranch_execz .LBB0_387
	s_waitcnt lgkmcnt(0)
	v_cvt_pk_bf16_f32 v33, v33, v36
	v_add_co_u32_e32 v36, vcc, 0x22000, v66
	s_nop 1
	v_addc_co_u32_e32 v37, vcc, 0, v67, vcc
	global_store_dword v[36:37], v33, off offset:192
.LBB0_387:
	s_or_b64 exec, exec, s[8:9]
	v_mul_f32_e32 v33, v38, v28
	v_mul_f32_e32 v33, v33, v32
	s_waitcnt lgkmcnt(0)
	s_nop 1
	v_mov_b32_dpp v36, v33 quad_perm:[1,0,3,2] row_mask:0xf bank_mask:0xf
	s_and_saveexec_b64 s[8:9], s[6:7]
	s_cbranch_execz .LBB0_389
	s_waitcnt lgkmcnt(0)
	v_cvt_pk_bf16_f32 v33, v33, v36
	v_add_co_u32_e32 v36, vcc, 0x24000, v66
	s_nop 1
	v_addc_co_u32_e32 v37, vcc, 0, v67, vcc
	global_store_dword v[36:37], v33, off offset:192
.LBB0_389:
	s_or_b64 exec, exec, s[8:9]
	v_mul_f32_e32 v33, v39, v29
	v_mul_f32_e32 v32, v33, v32
	s_nop 1
	v_mov_b32_dpp v33, v32 quad_perm:[1,0,3,2] row_mask:0xf bank_mask:0xf
	s_and_saveexec_b64 s[8:9], s[6:7]
	s_cbranch_execz .LBB0_391
	s_waitcnt lgkmcnt(0)
	v_cvt_pk_bf16_f32 v36, v32, v33
	v_add_co_u32_e32 v32, vcc, 0x26000, v66
	s_nop 1
	v_addc_co_u32_e32 v33, vcc, 0, v67, vcc
	global_store_dword v[32:33], v36, off offset:192
.LBB0_391:
	s_or_b64 exec, exec, s[8:9]
	global_load_dword v32, v[68:69], off offset:448
	s_waitcnt lgkmcnt(0)
	v_mul_f32_e32 v33, v48, v24
	s_waitcnt vmcnt(0)
	v_mul_f32_e32 v32, 0x3f4ccccd, v32
	v_mul_f32_e32 v33, v33, v32
	s_nop 1
	v_mov_b32_dpp v36, v33 quad_perm:[1,0,3,2] row_mask:0xf bank_mask:0xf
	s_and_saveexec_b64 s[8:9], s[6:7]
	s_cbranch_execz .LBB0_393
	s_waitcnt lgkmcnt(0)
	v_cvt_pk_bf16_f32 v33, v33, v36
	v_add_co_u32_e32 v36, vcc, 0x20000, v66
	s_nop 1
	v_addc_co_u32_e32 v37, vcc, 0, v67, vcc
	global_store_dword v[36:37], v33, off offset:224
.LBB0_393:
	s_or_b64 exec, exec, s[8:9]
	v_mul_f32_e32 v33, v49, v25
	v_mul_f32_e32 v33, v33, v32
	s_waitcnt lgkmcnt(0)
	s_nop 1
	v_mov_b32_dpp v36, v33 quad_perm:[1,0,3,2] row_mask:0xf bank_mask:0xf
	s_and_saveexec_b64 s[8:9], s[6:7]
	s_cbranch_execz .LBB0_395
	s_waitcnt lgkmcnt(0)
	v_cvt_pk_bf16_f32 v33, v33, v36
	v_add_co_u32_e32 v36, vcc, 0x22000, v66
	s_nop 1
	v_addc_co_u32_e32 v37, vcc, 0, v67, vcc
	global_store_dword v[36:37], v33, off offset:224
.LBB0_395:
	s_or_b64 exec, exec, s[8:9]
	v_mul_f32_e32 v33, v34, v28
	v_mul_f32_e32 v33, v33, v32
	s_nop 1
	v_mov_b32_dpp v34, v33 quad_perm:[1,0,3,2] row_mask:0xf bank_mask:0xf
	s_and_saveexec_b64 s[8:9], s[6:7]
	s_cbranch_execz .LBB0_397
	s_waitcnt lgkmcnt(0)
	v_add_co_u32_e32 v36, vcc, 0x24000, v66
	s_waitcnt lgkmcnt(0)
	v_cvt_pk_bf16_f32 v33, v33, v34
	s_nop 0
	v_addc_co_u32_e32 v37, vcc, 0, v67, vcc
	global_store_dword v[36:37], v33, off offset:224
.LBB0_397:
	s_or_b64 exec, exec, s[8:9]
	v_mul_f32_e32 v33, v35, v29
	v_mul_f32_e32 v32, v33, v32
	s_nop 1
	v_mov_b32_dpp v33, v32 quad_perm:[1,0,3,2] row_mask:0xf bank_mask:0xf
	s_and_saveexec_b64 s[8:9], s[6:7]
	s_cbranch_execz .LBB0_399
	s_waitcnt lgkmcnt(0)
	v_cvt_pk_bf16_f32 v34, v32, v33
	v_add_co_u32_e32 v32, vcc, 0x26000, v66
	s_nop 1
	v_addc_co_u32_e32 v33, vcc, 0, v67, vcc
	global_store_dword v[32:33], v34, off offset:224
.LBB0_399:
	s_or_b64 exec, exec, s[8:9]
	global_load_dword v32, v[68:69], off offset:512
	s_waitcnt lgkmcnt(0)
	v_mul_f32_e32 v33, v46, v24
	s_waitcnt vmcnt(0)
	v_mul_f32_e32 v32, 0x3f4ccccd, v32
	v_mul_f32_e32 v33, v33, v32
	s_nop 1
	v_mov_b32_dpp v34, v33 quad_perm:[1,0,3,2] row_mask:0xf bank_mask:0xf
	s_and_saveexec_b64 s[8:9], s[6:7]
	s_cbranch_execz .LBB0_401
	s_waitcnt lgkmcnt(0)
	v_cvt_pk_bf16_f32 v33, v33, v34
	v_add_co_u32_e32 v34, vcc, 0x20000, v66
	s_nop 1
	v_addc_co_u32_e32 v35, vcc, 0, v67, vcc
	global_store_dword v[34:35], v33, off offset:256
.LBB0_401:
	s_or_b64 exec, exec, s[8:9]
	v_mul_f32_e32 v33, v47, v25
	v_mul_f32_e32 v33, v33, v32
	s_waitcnt lgkmcnt(0)
	s_nop 1
	v_mov_b32_dpp v34, v33 quad_perm:[1,0,3,2] row_mask:0xf bank_mask:0xf
	s_and_saveexec_b64 s[8:9], s[6:7]
	s_cbranch_execz .LBB0_403
	s_waitcnt lgkmcnt(0)
	v_cvt_pk_bf16_f32 v33, v33, v34
	v_add_co_u32_e32 v34, vcc, 0x22000, v66
	s_nop 1
	v_addc_co_u32_e32 v35, vcc, 0, v67, vcc
	global_store_dword v[34:35], v33, off offset:256
.LBB0_403:
	s_or_b64 exec, exec, s[8:9]
	v_mul_f32_e32 v30, v30, v28
	v_mul_f32_e32 v30, v30, v32
	s_nop 1
	v_mov_b32_dpp v33, v30 quad_perm:[1,0,3,2] row_mask:0xf bank_mask:0xf
	s_and_saveexec_b64 s[8:9], s[6:7]
	s_cbranch_execz .LBB0_405
	s_waitcnt lgkmcnt(0)
	v_add_co_u32_e32 v34, vcc, 0x24000, v66
	s_waitcnt lgkmcnt(0)
	v_cvt_pk_bf16_f32 v30, v30, v33
	s_nop 0
	v_addc_co_u32_e32 v35, vcc, 0, v67, vcc
	global_store_dword v[34:35], v30, off offset:256
.LBB0_405:
	s_or_b64 exec, exec, s[8:9]
	v_mul_f32_e32 v30, v31, v29
	v_mul_f32_e32 v30, v30, v32
	s_nop 1
	v_mov_b32_dpp v31, v30 quad_perm:[1,0,3,2] row_mask:0xf bank_mask:0xf
	s_and_saveexec_b64 s[8:9], s[6:7]
	s_cbranch_execz .LBB0_407
	s_waitcnt lgkmcnt(0)
	v_cvt_pk_bf16_f32 v32, v30, v31
	v_add_co_u32_e32 v30, vcc, 0x26000, v66
	s_nop 1
	v_addc_co_u32_e32 v31, vcc, 0, v67, vcc
	global_store_dword v[30:31], v32, off offset:256
.LBB0_407:
	s_or_b64 exec, exec, s[8:9]
	global_load_dword v30, v[68:69], off offset:576
	s_waitcnt lgkmcnt(0)
	v_mul_f32_e32 v31, v44, v24
	s_waitcnt vmcnt(0)
	v_mul_f32_e32 v30, 0x3f4ccccd, v30
	v_mul_f32_e32 v31, v31, v30
	s_nop 1
	v_mov_b32_dpp v32, v31 quad_perm:[1,0,3,2] row_mask:0xf bank_mask:0xf
	s_and_saveexec_b64 s[8:9], s[6:7]
	s_cbranch_execz .LBB0_409
	s_waitcnt lgkmcnt(0)
	v_cvt_pk_bf16_f32 v31, v31, v32
	v_add_co_u32_e32 v32, vcc, 0x20000, v66
	s_nop 1
	v_addc_co_u32_e32 v33, vcc, 0, v67, vcc
	global_store_dword v[32:33], v31, off offset:288
.LBB0_409:
	s_or_b64 exec, exec, s[8:9]
	v_mul_f32_e32 v31, v45, v25
	v_mul_f32_e32 v31, v31, v30
	s_waitcnt lgkmcnt(0)
	s_nop 1
	v_mov_b32_dpp v32, v31 quad_perm:[1,0,3,2] row_mask:0xf bank_mask:0xf
	s_and_saveexec_b64 s[8:9], s[6:7]
	s_cbranch_execz .LBB0_411
	s_waitcnt lgkmcnt(0)
	v_cvt_pk_bf16_f32 v31, v31, v32
	v_add_co_u32_e32 v32, vcc, 0x22000, v66
	s_nop 1
	v_addc_co_u32_e32 v33, vcc, 0, v67, vcc
	global_store_dword v[32:33], v31, off offset:288
.LBB0_411:
	s_or_b64 exec, exec, s[8:9]
	v_mul_f32_e32 v26, v26, v28
	v_mul_f32_e32 v26, v26, v30
	s_nop 1
	v_mov_b32_dpp v31, v26 quad_perm:[1,0,3,2] row_mask:0xf bank_mask:0xf
	s_and_saveexec_b64 s[8:9], s[6:7]
	s_cbranch_execz .LBB0_413
	s_waitcnt lgkmcnt(0)
	v_add_co_u32_e32 v32, vcc, 0x24000, v66
	s_waitcnt lgkmcnt(0)
	v_cvt_pk_bf16_f32 v26, v26, v31
	s_nop 0
	v_addc_co_u32_e32 v33, vcc, 0, v67, vcc
	global_store_dword v[32:33], v26, off offset:288
.LBB0_413:
	s_or_b64 exec, exec, s[8:9]
	v_mul_f32_e32 v26, v27, v29
	v_mul_f32_e32 v26, v26, v30
	s_nop 1
	v_mov_b32_dpp v27, v26 quad_perm:[1,0,3,2] row_mask:0xf bank_mask:0xf
	s_and_saveexec_b64 s[8:9], s[6:7]
	s_cbranch_execz .LBB0_415
	s_waitcnt lgkmcnt(0)
	v_cvt_pk_bf16_f32 v30, v26, v27
	v_add_co_u32_e32 v26, vcc, 0x26000, v66
	s_nop 1
	v_addc_co_u32_e32 v27, vcc, 0, v67, vcc
	global_store_dword v[26:27], v30, off offset:288
.LBB0_415:
	s_or_b64 exec, exec, s[8:9]
	global_load_dword v26, v[68:69], off offset:640
	s_waitcnt lgkmcnt(0)
	v_mul_f32_e32 v27, v42, v24
	s_waitcnt vmcnt(0)
	v_mul_f32_e32 v26, 0x3f4ccccd, v26
	v_mul_f32_e32 v27, v27, v26
	s_nop 1
	v_mov_b32_dpp v30, v27 quad_perm:[1,0,3,2] row_mask:0xf bank_mask:0xf
	s_and_saveexec_b64 s[8:9], s[6:7]
	s_cbranch_execz .LBB0_417
	s_waitcnt lgkmcnt(0)
	v_cvt_pk_bf16_f32 v27, v27, v30
	v_add_co_u32_e32 v30, vcc, 0x20000, v66
	s_nop 1
	v_addc_co_u32_e32 v31, vcc, 0, v67, vcc
	global_store_dword v[30:31], v27, off offset:320
.LBB0_417:
	s_or_b64 exec, exec, s[8:9]
	v_mul_f32_e32 v27, v43, v25
	v_mul_f32_e32 v27, v27, v26
	s_waitcnt lgkmcnt(0)
	s_nop 1
	v_mov_b32_dpp v30, v27 quad_perm:[1,0,3,2] row_mask:0xf bank_mask:0xf
	s_and_saveexec_b64 s[8:9], s[6:7]
	s_cbranch_execz .LBB0_419
	s_waitcnt lgkmcnt(0)
	v_cvt_pk_bf16_f32 v27, v27, v30
	v_add_co_u32_e32 v30, vcc, 0x22000, v66
	s_nop 1
	v_addc_co_u32_e32 v31, vcc, 0, v67, vcc
	global_store_dword v[30:31], v27, off offset:320
.LBB0_419:
	s_or_b64 exec, exec, s[8:9]
	v_mul_f32_e32 v22, v22, v28
	v_mul_f32_e32 v22, v22, v26
	s_nop 1
	v_mov_b32_dpp v27, v22 quad_perm:[1,0,3,2] row_mask:0xf bank_mask:0xf
	s_and_saveexec_b64 s[8:9], s[6:7]
	s_cbranch_execz .LBB0_421
	s_waitcnt lgkmcnt(0)
	v_add_co_u32_e32 v30, vcc, 0x24000, v66
	s_waitcnt lgkmcnt(0)
	v_cvt_pk_bf16_f32 v22, v22, v27
	s_nop 0
	v_addc_co_u32_e32 v31, vcc, 0, v67, vcc
	global_store_dword v[30:31], v22, off offset:320
.LBB0_421:
	s_or_b64 exec, exec, s[8:9]
	v_mul_f32_e32 v22, v23, v29
	v_mul_f32_e32 v22, v22, v26
	s_nop 1
	v_mov_b32_dpp v23, v22 quad_perm:[1,0,3,2] row_mask:0xf bank_mask:0xf
	s_and_saveexec_b64 s[8:9], s[6:7]
	s_cbranch_execz .LBB0_423
	s_waitcnt lgkmcnt(0)
	v_cvt_pk_bf16_f32 v26, v22, v23
	v_add_co_u32_e32 v22, vcc, 0x26000, v66
	s_nop 1
	v_addc_co_u32_e32 v23, vcc, 0, v67, vcc
	global_store_dword v[22:23], v26, off offset:320
.LBB0_423:
	s_or_b64 exec, exec, s[8:9]
	global_load_dword v22, v[68:69], off offset:704
	v_mul_f32_e32 v18, v18, v24
	s_waitcnt vmcnt(0)
	v_mul_f32_e32 v22, 0x3f4ccccd, v22
	v_mul_f32_e32 v18, v18, v22
	s_waitcnt lgkmcnt(0)
	s_nop 1
	v_mov_b32_dpp v23, v18 quad_perm:[1,0,3,2] row_mask:0xf bank_mask:0xf
	s_and_saveexec_b64 s[8:9], s[6:7]
	s_cbranch_execz .LBB0_425
	v_add_co_u32_e32 v26, vcc, 0x20000, v66
	s_waitcnt lgkmcnt(0)
	v_cvt_pk_bf16_f32 v18, v18, v23
	s_nop 0
	v_addc_co_u32_e32 v27, vcc, 0, v67, vcc
	global_store_dword v[26:27], v18, off offset:352
.LBB0_425:
	s_or_b64 exec, exec, s[8:9]
	v_mul_f32_e32 v18, v19, v25
	v_mul_f32_e32 v18, v18, v22
	s_nop 1
	v_mov_b32_dpp v19, v18 quad_perm:[1,0,3,2] row_mask:0xf bank_mask:0xf
	s_and_saveexec_b64 s[8:9], s[6:7]
	s_cbranch_execz .LBB0_427
	s_waitcnt lgkmcnt(0)
	v_cvt_pk_bf16_f32 v23, v18, v19
	v_add_co_u32_e32 v18, vcc, 0x22000, v66
	s_nop 1
	v_addc_co_u32_e32 v19, vcc, 0, v67, vcc
	global_store_dword v[18:19], v23, off offset:352
.LBB0_427:
	s_or_b64 exec, exec, s[8:9]
	v_mul_f32_e32 v18, v20, v28
	v_mul_f32_e32 v18, v18, v22
	s_waitcnt lgkmcnt(0)
	s_nop 1
	v_mov_b32_dpp v19, v18 quad_perm:[1,0,3,2] row_mask:0xf bank_mask:0xf
	s_and_saveexec_b64 s[8:9], s[6:7]
	s_cbranch_execz .LBB0_429
	s_waitcnt lgkmcnt(0)
	v_cvt_pk_bf16_f32 v20, v18, v19
	v_add_co_u32_e32 v18, vcc, 0x24000, v66
	s_nop 1
	v_addc_co_u32_e32 v19, vcc, 0, v67, vcc
	global_store_dword v[18:19], v20, off offset:352
.LBB0_429:
	s_or_b64 exec, exec, s[8:9]
	v_mul_f32_e32 v18, v21, v29
	v_mul_f32_e32 v18, v18, v22
	s_waitcnt lgkmcnt(0)
	s_nop 1
	v_mov_b32_dpp v19, v18 quad_perm:[1,0,3,2] row_mask:0xf bank_mask:0xf
	s_and_saveexec_b64 s[8:9], s[6:7]
	s_cbranch_execz .LBB0_431
	s_waitcnt lgkmcnt(0)
	v_cvt_pk_bf16_f32 v20, v18, v19
	v_add_co_u32_e32 v18, vcc, 0x26000, v66
	s_nop 1
	v_addc_co_u32_e32 v19, vcc, 0, v67, vcc
	global_store_dword v[18:19], v20, off offset:352
.LBB0_431:
	s_or_b64 exec, exec, s[8:9]
	global_load_dword v18, v[68:69], off offset:768
	v_mul_f32_e32 v14, v14, v24
	s_waitcnt vmcnt(0)
	v_mul_f32_e32 v18, 0x3f4ccccd, v18
	v_mul_f32_e32 v14, v14, v18
	s_waitcnt lgkmcnt(0)
	s_nop 1
	v_mov_b32_dpp v19, v14 quad_perm:[1,0,3,2] row_mask:0xf bank_mask:0xf
	s_and_saveexec_b64 s[8:9], s[6:7]
	s_cbranch_execz .LBB0_433
	v_add_co_u32_e32 v20, vcc, 0x20000, v66
	s_waitcnt lgkmcnt(0)
	v_cvt_pk_bf16_f32 v14, v14, v19
	s_nop 0
	v_addc_co_u32_e32 v21, vcc, 0, v67, vcc
	global_store_dword v[20:21], v14, off offset:384
.LBB0_433:
	s_or_b64 exec, exec, s[8:9]
	v_mul_f32_e32 v14, v15, v25
	v_mul_f32_e32 v14, v14, v18
	s_nop 1
	v_mov_b32_dpp v15, v14 quad_perm:[1,0,3,2] row_mask:0xf bank_mask:0xf
	s_and_saveexec_b64 s[8:9], s[6:7]
	s_cbranch_execz .LBB0_435
	s_waitcnt lgkmcnt(0)
	v_cvt_pk_bf16_f32 v19, v14, v15
	v_add_co_u32_e32 v14, vcc, 0x22000, v66
	s_nop 1
	v_addc_co_u32_e32 v15, vcc, 0, v67, vcc
	global_store_dword v[14:15], v19, off offset:384
.LBB0_435:
	s_or_b64 exec, exec, s[8:9]
	v_mul_f32_e32 v14, v16, v28
	v_mul_f32_e32 v14, v14, v18
	s_waitcnt lgkmcnt(0)
	s_nop 1
	v_mov_b32_dpp v15, v14 quad_perm:[1,0,3,2] row_mask:0xf bank_mask:0xf
	s_and_saveexec_b64 s[8:9], s[6:7]
	s_cbranch_execz .LBB0_437
	s_waitcnt lgkmcnt(0)
	v_cvt_pk_bf16_f32 v16, v14, v15
	v_add_co_u32_e32 v14, vcc, 0x24000, v66
	s_nop 1
	v_addc_co_u32_e32 v15, vcc, 0, v67, vcc
	global_store_dword v[14:15], v16, off offset:384
.LBB0_437:
	s_or_b64 exec, exec, s[8:9]
	v_mul_f32_e32 v14, v17, v29
	v_mul_f32_e32 v14, v14, v18
	s_waitcnt lgkmcnt(0)
	s_nop 1
	v_mov_b32_dpp v15, v14 quad_perm:[1,0,3,2] row_mask:0xf bank_mask:0xf
	s_and_saveexec_b64 s[8:9], s[6:7]
	s_cbranch_execz .LBB0_439
	s_waitcnt lgkmcnt(0)
	v_cvt_pk_bf16_f32 v16, v14, v15
	v_add_co_u32_e32 v14, vcc, 0x26000, v66
	s_nop 1
	v_addc_co_u32_e32 v15, vcc, 0, v67, vcc
	global_store_dword v[14:15], v16, off offset:384
.LBB0_439:
	s_or_b64 exec, exec, s[8:9]
	global_load_dword v14, v[68:69], off offset:832
	v_mul_f32_e32 v10, v10, v24
	s_waitcnt vmcnt(0)
	v_mul_f32_e32 v14, 0x3f4ccccd, v14
	v_mul_f32_e32 v10, v10, v14
	s_waitcnt lgkmcnt(0)
	s_nop 1
	v_mov_b32_dpp v15, v10 quad_perm:[1,0,3,2] row_mask:0xf bank_mask:0xf
	s_and_saveexec_b64 s[8:9], s[6:7]
	s_cbranch_execz .LBB0_441
	v_add_co_u32_e32 v16, vcc, 0x20000, v66
	s_waitcnt lgkmcnt(0)
	v_cvt_pk_bf16_f32 v10, v10, v15
	s_nop 0
	v_addc_co_u32_e32 v17, vcc, 0, v67, vcc
	global_store_dword v[16:17], v10, off offset:416
.LBB0_441:
	s_or_b64 exec, exec, s[8:9]
	v_mul_f32_e32 v10, v11, v25
	v_mul_f32_e32 v10, v10, v14
	s_nop 1
	v_mov_b32_dpp v11, v10 quad_perm:[1,0,3,2] row_mask:0xf bank_mask:0xf
	s_and_saveexec_b64 s[8:9], s[6:7]
	s_cbranch_execz .LBB0_443
	s_waitcnt lgkmcnt(0)
	v_cvt_pk_bf16_f32 v15, v10, v11
	v_add_co_u32_e32 v10, vcc, 0x22000, v66
	s_nop 1
	v_addc_co_u32_e32 v11, vcc, 0, v67, vcc
	global_store_dword v[10:11], v15, off offset:416
.LBB0_443:
	s_or_b64 exec, exec, s[8:9]
	v_mul_f32_e32 v10, v12, v28
	v_mul_f32_e32 v10, v10, v14
	s_waitcnt lgkmcnt(0)
	s_nop 1
	v_mov_b32_dpp v11, v10 quad_perm:[1,0,3,2] row_mask:0xf bank_mask:0xf
	s_and_saveexec_b64 s[8:9], s[6:7]
	s_cbranch_execz .LBB0_445
	s_waitcnt lgkmcnt(0)
	v_cvt_pk_bf16_f32 v12, v10, v11
	v_add_co_u32_e32 v10, vcc, 0x24000, v66
	s_nop 1
	v_addc_co_u32_e32 v11, vcc, 0, v67, vcc
	global_store_dword v[10:11], v12, off offset:416
.LBB0_445:
	s_or_b64 exec, exec, s[8:9]
	v_mul_f32_e32 v10, v13, v29
	v_mul_f32_e32 v10, v10, v14
	s_waitcnt lgkmcnt(0)
	s_nop 1
	v_mov_b32_dpp v11, v10 quad_perm:[1,0,3,2] row_mask:0xf bank_mask:0xf
	s_and_saveexec_b64 s[8:9], s[6:7]
	s_cbranch_execz .LBB0_447
	s_waitcnt lgkmcnt(0)
	v_cvt_pk_bf16_f32 v12, v10, v11
	v_add_co_u32_e32 v10, vcc, 0x26000, v66
	s_nop 1
	v_addc_co_u32_e32 v11, vcc, 0, v67, vcc
	global_store_dword v[10:11], v12, off offset:416
.LBB0_447:
	s_or_b64 exec, exec, s[8:9]
	global_load_dword v10, v[68:69], off offset:896
	v_mul_f32_e32 v6, v6, v24
	s_waitcnt vmcnt(0)
	v_mul_f32_e32 v10, 0x3f4ccccd, v10
	v_mul_f32_e32 v6, v6, v10
	s_waitcnt lgkmcnt(0)
	s_nop 1
	v_mov_b32_dpp v11, v6 quad_perm:[1,0,3,2] row_mask:0xf bank_mask:0xf
	s_and_saveexec_b64 s[8:9], s[6:7]
	s_cbranch_execz .LBB0_449
	v_add_co_u32_e32 v12, vcc, 0x20000, v66
	s_waitcnt lgkmcnt(0)
	v_cvt_pk_bf16_f32 v6, v6, v11
	s_nop 0
	v_addc_co_u32_e32 v13, vcc, 0, v67, vcc
	global_store_dword v[12:13], v6, off offset:448
.LBB0_449:
	s_or_b64 exec, exec, s[8:9]
	v_mul_f32_e32 v6, v7, v25
	v_mul_f32_e32 v6, v6, v10
	s_nop 1
	v_mov_b32_dpp v7, v6 quad_perm:[1,0,3,2] row_mask:0xf bank_mask:0xf
	s_and_saveexec_b64 s[8:9], s[6:7]
	s_cbranch_execz .LBB0_451
	s_waitcnt lgkmcnt(0)
	v_cvt_pk_bf16_f32 v11, v6, v7
	v_add_co_u32_e32 v6, vcc, 0x22000, v66
	s_nop 1
	v_addc_co_u32_e32 v7, vcc, 0, v67, vcc
	global_store_dword v[6:7], v11, off offset:448
.LBB0_451:
	s_or_b64 exec, exec, s[8:9]
	v_mul_f32_e32 v6, v8, v28
	v_mul_f32_e32 v6, v6, v10
	s_waitcnt lgkmcnt(0)
	s_nop 1
	v_mov_b32_dpp v7, v6 quad_perm:[1,0,3,2] row_mask:0xf bank_mask:0xf
	s_and_saveexec_b64 s[8:9], s[6:7]
	s_cbranch_execz .LBB0_453
	s_waitcnt lgkmcnt(0)
	v_cvt_pk_bf16_f32 v8, v6, v7
	v_add_co_u32_e32 v6, vcc, 0x24000, v66
	s_nop 1
	v_addc_co_u32_e32 v7, vcc, 0, v67, vcc
	global_store_dword v[6:7], v8, off offset:448
.LBB0_453:
	s_or_b64 exec, exec, s[8:9]
	v_mul_f32_e32 v6, v9, v29
	v_mul_f32_e32 v6, v6, v10
	s_waitcnt lgkmcnt(0)
	s_nop 1
	v_mov_b32_dpp v7, v6 quad_perm:[1,0,3,2] row_mask:0xf bank_mask:0xf
	s_and_saveexec_b64 s[8:9], s[6:7]
	s_cbranch_execz .LBB0_455
	s_waitcnt lgkmcnt(0)
	v_cvt_pk_bf16_f32 v8, v6, v7
	v_add_co_u32_e32 v6, vcc, 0x26000, v66
	s_nop 1
	v_addc_co_u32_e32 v7, vcc, 0, v67, vcc
	global_store_dword v[6:7], v8, off offset:448
.LBB0_455:
	s_or_b64 exec, exec, s[8:9]
	global_load_dword v6, v[68:69], off offset:960
	v_mul_f32_e32 v2, v2, v24
	s_waitcnt vmcnt(0)
	v_mul_f32_e32 v6, 0x3f4ccccd, v6
	v_mul_f32_e32 v2, v2, v6
	s_waitcnt lgkmcnt(0)
	s_nop 1
	v_mov_b32_dpp v7, v2 quad_perm:[1,0,3,2] row_mask:0xf bank_mask:0xf
	s_and_saveexec_b64 s[8:9], s[6:7]
	s_cbranch_execz .LBB0_457
	v_add_co_u32_e32 v8, vcc, 0x20000, v66
	s_waitcnt lgkmcnt(0)
	v_cvt_pk_bf16_f32 v2, v2, v7
	s_nop 0
	v_addc_co_u32_e32 v9, vcc, 0, v67, vcc
	global_store_dword v[8:9], v2, off offset:480
.LBB0_457:
	s_or_b64 exec, exec, s[8:9]
	v_mul_f32_e32 v2, v3, v25
	v_mul_f32_e32 v2, v2, v6
	s_nop 1
	v_mov_b32_dpp v3, v2 quad_perm:[1,0,3,2] row_mask:0xf bank_mask:0xf
	s_and_saveexec_b64 s[8:9], s[6:7]
	s_cbranch_execz .LBB0_459
	s_waitcnt lgkmcnt(0)
	v_cvt_pk_bf16_f32 v7, v2, v3
	v_add_co_u32_e32 v2, vcc, 0x22000, v66
	s_nop 1
	v_addc_co_u32_e32 v3, vcc, 0, v67, vcc
	global_store_dword v[2:3], v7, off offset:480
.LBB0_459:
	s_or_b64 exec, exec, s[8:9]
	v_mul_f32_e32 v2, v4, v28
	v_mul_f32_e32 v2, v2, v6
	s_waitcnt lgkmcnt(0)
	s_nop 1
	v_mov_b32_dpp v3, v2 quad_perm:[1,0,3,2] row_mask:0xf bank_mask:0xf
	s_and_saveexec_b64 s[8:9], s[6:7]
	s_cbranch_execz .LBB0_461
	s_waitcnt lgkmcnt(0)
	v_cvt_pk_bf16_f32 v4, v2, v3
	v_add_co_u32_e32 v2, vcc, 0x24000, v66
	s_nop 1
	v_addc_co_u32_e32 v3, vcc, 0, v67, vcc
	global_store_dword v[2:3], v4, off offset:480
.LBB0_461:
	s_or_b64 exec, exec, s[8:9]
	v_mul_f32_e32 v2, v5, v29
	v_mul_f32_e32 v2, v2, v6
	s_waitcnt lgkmcnt(0)
	s_nop 1
	v_mov_b32_dpp v3, v2 quad_perm:[1,0,3,2] row_mask:0xf bank_mask:0xf
	s_and_saveexec_b64 s[8:9], s[6:7]
	s_cbranch_execz .LBB0_180
	s_waitcnt lgkmcnt(0)
	v_cvt_pk_bf16_f32 v4, v2, v3
	v_add_co_u32_e32 v2, vcc, 0x26000, v66
	s_nop 1
	v_addc_co_u32_e32 v3, vcc, 0, v67, vcc
	global_store_dword v[2:3], v4, off offset:480
	s_branch .LBB0_180
